# nt hint on the SSD states phase's input loads on top of the P0 nt version
# baseline (speedup 1.0000x reference)
; __device__ __forceinline__ void conv_load(ConvRaw& R, const bf16* XBC, int b, int c, int col0, int rg) {
;     const int r0 = 8 * rg;
; #pragma unroll
;     for (int i = 0; i < 10; ++i) { int t = c * 128 + r0 - 1 + i; t = t < 0 ? 0 : (t > SEQ - 1 ? SEQ - 1 : t); R.r[i] = *(const u32x4*)(XBC + ((size_t)b * SEQ + t) * XBCW + col0); }
;     if (c == 0 && rg == 0) R.r[0] = (u32x4){0u, 0u, 0u, 0u};
;     if (c == 63 && rg == 15) R.r[9] = (u32x4){0u, 0u, 0u, 0u};
; template <int NR>
; __device__ __forceinline__ void conv_load_n(ConvRawN<NR>& R, const bf16* XBC, int b, int c, int col0, int rg) {
;     const int r0 = NR * rg;
; #pragma unroll
;     for (int i = 0; i < NR + 2; ++i) { int t = c * 128 + r0 - 1 + i; t = t < 0 ? 0 : (t > SEQ - 1 ? SEQ - 1 : t); R.r[i] = *(const u32x4*)(XBC + ((size_t)b * SEQ + t) * XBCW + col0); }
;     if (c == 0 && r0 == 0) R.r[0] = (u32x4){0u, 0u, 0u, 0u};
;     if (c == 63 && r0 + NR == 128) R.r[NR + 1] = (u32x4){0u, 0u, 0u, 0u};
.LBB0_562:
	s_bfe_u32 s84, s83, 0x60002
	s_bfe_u32 s0, s83, 0x10001
	v_mbcnt_lo_u32_b32 v0, -1, 0
	v_mbcnt_hi_u32_b32 v0, -1, v0
	s_lshl_b32 s2, s83, 2
	v_add_u32_e32 v100, s60, v0
	s_lshl_b32 s1, s0, 3
	s_and_b32 s2, s2, 4
	v_ashrrev_i32_e32 v99, 4, v100
	s_lshl_b32 s85, s84, 7
	s_ashr_i32 s70, s83, 8
	s_or_b32 s16, s1, s2
	v_and_b32_e32 v98, 15, v100
	s_lshl_b32 s0, s0, 7
	v_lshlrev_b32_e32 v2, 2, v99
	s_add_i32 s2, s85, -1
	v_lshl_or_b32 v0, v98, 3, s0
	v_add_u32_e32 v4, s2, v2
	s_ashr_i32 s71, s70, 31
	v_or_b32_e32 v56, 0x400, v0
	s_lshl_b64 s[4:5], s[70:71], 13
	v_med3_i32 v0, v4, 0, v132
	v_add_u32_e32 v2, s85, v2
	v_or_b32_e32 v0, s4, v0
	v_med3_i32 v2, v2, 0, v132
	s_waitcnt lgkmcnt(0)
	v_mad_u64_u32 v[0:1], s[0:1], v0, s77, v[130:131]
	v_or_b32_e32 v2, s4, v2
	v_mad_i32_i24 v1, s5, v133, v1
	v_lshlrev_b32_e32 v128, 1, v56
	v_mad_u64_u32 v[2:3], s[0:1], v2, s77, v[130:131]
	v_lshl_add_u64 v[0:1], v[0:1], 0, v[128:129]
	v_mad_i32_i24 v3, s5, v133, v3
	v_lshl_add_u64 v[2:3], v[2:3], 0, v[128:129]
	v_lshl_add_u64 v[146:147], v[0:1], 0, s[100:101]
	global_load_dwordx4 v[88:91], v[0:1], off nt
	v_lshl_add_u64 v[148:149], v[2:3], 0, s[100:101]
	global_load_dwordx4 v[48:51], v[2:3], off nt
	v_max_i32_e32 v0, -2, v4
	v_add_u32_e32 v0, 2, v0
	v_max_i32_e32 v2, -3, v4
	v_min_u32_e32 v0, 0x1fff, v0
	v_add_u32_e32 v2, 3, v2
	v_or_b32_e32 v0, s4, v0
	v_min_u32_e32 v2, 0x1fff, v2
	v_mad_u64_u32 v[0:1], s[0:1], v0, s77, v[130:131]
	v_or_b32_e32 v2, s4, v2
	v_mad_i32_i24 v1, s5, v133, v1
	v_mad_u64_u32 v[2:3], s[0:1], v2, s77, v[130:131]
	v_lshl_add_u64 v[0:1], v[0:1], 0, v[128:129]
	v_mad_i32_i24 v3, s5, v133, v3
	v_lshl_add_u64 v[2:3], v[2:3], 0, v[128:129]
	v_lshl_add_u64 v[150:151], v[0:1], 0, s[100:101]
	global_load_dwordx4 v[52:55], v[0:1], off nt
	v_lshl_add_u64 v[152:153], v[2:3], 0, s[100:101]
	global_load_dwordx4 v[44:47], v[2:3], off nt
	v_max_i32_e32 v0, -4, v4
	v_add_u32_e32 v0, 4, v0
	v_max_i32_e32 v2, -5, v4
	v_min_u32_e32 v0, 0x1fff, v0
	v_add_u32_e32 v2, 5, v2
	v_or_b32_e32 v0, s4, v0
	v_min_u32_e32 v2, 0x1fff, v2
	v_mad_u64_u32 v[0:1], s[0:1], v0, s77, v[130:131]
	v_or_b32_e32 v2, s4, v2
	v_mad_i32_i24 v1, s5, v133, v1
	v_mad_u64_u32 v[2:3], s[0:1], v2, s77, v[130:131]
	v_ashrrev_i32_e32 v103, 7, v100
	v_and_b32_e32 v101, 7, v100
	v_bfe_u32 v102, v100, 3, 4
	v_lshl_add_u64 v[0:1], v[0:1], 0, v[128:129]
	v_mad_i32_i24 v3, s5, v133, v3
	v_lshl_add_u64 v[2:3], v[2:3], 0, v[128:129]
	v_lshl_add_u64 v[154:155], v[0:1], 0, s[100:101]
	global_load_dwordx4 v[40:43], v[0:1], off nt
	v_lshl_add_u64 v[156:157], v[2:3], 0, s[100:101]
	global_load_dwordx4 v[92:95], v[2:3], off nt
	v_add_u32_e32 v0, s16, v103
	v_lshlrev_b32_e32 v1, 3, v101
	v_lshlrev_b32_e32 v6, 3, v102
	v_lshl_or_b32 v96, v0, 6, v1
	v_add_u32_e32 v38, s2, v6
	v_ashrrev_i32_e32 v97, 31, v96
	v_max_i32_e32 v128, 0, v38
	v_lshl_add_u64 v[0:1], v[96:97], 1, s[10:11]
	v_lshl_add_u64 v[2:3], s[4:5], 0, v[128:129]
	v_mad_u64_u32 v[4:5], s[0:1], v2, s77, v[0:1]
	v_or_b32_e32 v2, s85, v6
	v_or_b32_e32 v2, s4, v2
	v_mad_i32_i24 v5, v3, s77, v5
	v_mad_u64_u32 v[2:3], s[0:1], v2, s77, v[0:1]
	v_mad_i32_i24 v3, s5, v133, v3
	v_add_u32_e32 v128, 2, v38
	v_lshl_add_u64 v[158:159], v[4:5], 0, s[100:101]
	global_load_dwordx4 v[32:35], v[4:5], off nt
	v_lshl_add_u64 v[160:161], v[2:3], 0, s[100:101]
	global_load_dwordx4 v[24:27], v[2:3], off nt
	v_lshl_add_u64 v[2:3], s[4:5], 0, v[128:129]
	v_mad_u64_u32 v[4:5], s[0:1], v2, s77, v[0:1]
	v_add_u32_e32 v128, 3, v38
	v_mad_i32_i24 v5, v3, s77, v5
	v_lshl_add_u64 v[2:3], s[4:5], 0, v[128:129]
	v_mad_u64_u32 v[6:7], s[0:1], v2, s77, v[0:1]
	v_add_u32_e32 v128, 4, v38
	v_mad_i32_i24 v7, v3, s77, v7
	v_lshl_add_u64 v[2:3], s[4:5], 0, v[128:129]
	v_lshl_add_u64 v[162:163], v[4:5], 0, s[100:101]
	global_load_dwordx4 v[28:31], v[4:5], off nt
	v_lshl_add_u64 v[164:165], v[6:7], 0, s[100:101]
	global_load_dwordx4 v[20:23], v[6:7], off nt
	v_mad_u64_u32 v[4:5], s[0:1], v2, s77, v[0:1]
	v_add_u32_e32 v128, 5, v38
	v_mad_i32_i24 v5, v3, s77, v5
	v_lshl_add_u64 v[2:3], s[4:5], 0, v[128:129]
	v_mad_u64_u32 v[6:7], s[0:1], v2, s77, v[0:1]
	v_add_u32_e32 v128, 6, v38
	v_mad_i32_i24 v7, v3, s77, v7
	v_lshl_add_u64 v[2:3], s[4:5], 0, v[128:129]
	v_lshl_add_u64 v[166:167], v[4:5], 0, s[100:101]
	global_load_dwordx4 v[16:19], v[4:5], off nt
	v_lshl_add_u64 v[168:169], v[6:7], 0, s[100:101]
	global_load_dwordx4 v[12:15], v[6:7], off nt
	v_mad_u64_u32 v[4:5], s[0:1], v2, s77, v[0:1]
	v_add_u32_e32 v128, 7, v38
	v_mad_i32_i24 v5, v3, s77, v5
	v_lshl_add_u64 v[2:3], s[4:5], 0, v[128:129]
	v_mad_u64_u32 v[6:7], s[0:1], v2, s77, v[0:1]
	v_add_u32_e32 v128, 8, v38
	v_mad_i32_i24 v7, v3, s77, v7
	v_lshl_add_u64 v[2:3], s[4:5], 0, v[128:129]
	v_mad_u64_u32 v[36:37], s[0:1], v2, s77, v[0:1]
	v_add_u32_e32 v2, 9, v38
	v_min_u32_e32 v2, 0x1fff, v2
	v_or_b32_e32 v2, s4, v2
	v_mad_u64_u32 v[38:39], s[0:1], v2, s77, v[0:1]
	v_mad_i32_i24 v37, v3, s77, v37
	v_mad_i32_i24 v39, s5, v133, v39
	v_lshl_add_u64 v[170:171], v[4:5], 0, s[100:101]
	global_load_dwordx4 v[8:11], v[4:5], off nt
	s_nop 0
	v_lshl_add_u64 v[172:173], v[6:7], 0, s[100:101]
	global_load_dwordx4 v[4:7], v[6:7], off nt
	s_nop 0
	v_lshl_add_u64 v[174:175], v[36:37], 0, s[100:101]
	global_load_dwordx4 v[0:3], v[36:37], off nt
	s_nop 0
	v_lshl_add_u64 v[176:177], v[38:39], 0, s[100:101]
	global_load_dwordx4 v[36:39], v[38:39], off nt
	v_and_b32_e32 v104, 63, v100
	v_readlane_b32 s0, v252, 5
	s_nop 1
	v_or_b32_e32 v57, s0, v104
	v_cmp_eq_u32_e32 vcc, 0, v57
	s_and_saveexec_b64 s[0:1], vcc
	s_cbranch_execz .LBB0_571
	s_lshl_b32 s2, s70, 7
	s_lshl_b32 s3, s84, 1
	s_or_b32 s2, s3, s2
	s_ashr_i32 s3, s2, 31
	s_lshl_b64 s[2:3], s[2:3], 2
	s_add_u32 s2, s33, s2
	s_addc_u32 s3, s34, s3
	s_mov_b32 s72, 0x400001
	s_branch .LBB0_565

;     __device__ __forceinline__ int lane_() const { return hw_lane(); }
; __device__ __forceinline__ unsigned cvtpk(float lo, float hi) { f32x2_t v = {lo, hi}; bf16x2_t b = __builtin_convertvector(v, bf16x2_t); return __builtin_bit_cast(unsigned, b); }
; __device__ __forceinline__ float lo16(unsigned u) { return __uint_as_float(u << 16); }
; __device__ __forceinline__ float hi16(unsigned u) { return __uint_as_float(u & 0xffff0000u); }
; template <int NR, class Put>
; __device__ __forceinline__ void conv_compute_n(const ConvRawN<NR>& R, const float* cw, const float* cb, int col0, int rg, const Put& put) {
;     const f32x4 w0a = *(const f32x4*)(cw + col0), w0b = *(const f32x4*)(cw + col0 + 4), w1a = *(const f32x4*)(cw + XBCW + col0), w1b = *(const f32x4*)(cw + XBCW + col0 + 4);
;     const f32x4 w2a = *(const f32x4*)(cw + 2 * XBCW + col0), w2b = *(const f32x4*)(cw + 2 * XBCW + col0 + 4), ba = *(const f32x4*)(cb + col0), bb = *(const f32x4*)(cb + col0 + 4);
;     const int r0 = NR * rg;
; #pragma unroll
;     for (int rr = 0; rr < NR; ++rr) {
;         const u32x4 xm = R.r[rr], x0 = R.r[rr + 1], xp = R.r[rr + 2]; u32x4 o;
; #pragma unroll
;         for (int e = 0; e < 4; ++e) {
;             const float wl0 = e < 2 ? w0a[2 * e] : w0b[2 * e - 4], wh0 = e < 2 ? w0a[2 * e + 1] : w0b[2 * e - 3];
;             const float wl1 = e < 2 ? w1a[2 * e] : w1b[2 * e - 4], wh1 = e < 2 ? w1a[2 * e + 1] : w1b[2 * e - 3];
;             const float wl2 = e < 2 ? w2a[2 * e] : w2b[2 * e - 4], wh2 = e < 2 ? w2a[2 * e + 1] : w2b[2 * e - 3];
;             const float bl = e < 2 ? ba[2 * e] : bb[2 * e - 4], bh = e < 2 ? ba[2 * e + 1] : bb[2 * e - 3];
;             const float vl = bl + wl0 * lo16(xm[e]) + wl1 * lo16(x0[e]) + wl2 * lo16(xp[e]);
;             const float vh = bh + wh0 * hi16(xm[e]) + wh1 * hi16(x0[e]) + wh2 * hi16(xp[e]);
;             o[e] = cvtpk(silu_fast(vl), silu_fast(vh));
;         }
;         put(r0 + rr, o);
;     }
; }
; __device__ __forceinline__ void vec_load(Frame& F, const Ptrs& P, int b, int c, int h0, float& v0, float& v1) {
;     const float* DT = (const float*)(P.ws + WS_DT);
;     const int lane = F.lane_(), hl = F.wave >> 1, dir = F.wave & 1, h = h0 + hl;
;     const size_t row0 = (size_t)b * SEQ + c * 128;
;     v0 = DT[(row0 + lane) * 32 + dir * 16 + h]; v1 = DT[(row0 + 64 + lane) * 32 + dir * 16 + h];
; }
.LBB0_571:
	s_or_b64 exec, exec, s[0:1]
	v_lshlrev_b32_e32 v56, 2, v56
	s_barrier
	v_mbcnt_lo_u32_b32 v106, -1, 0
	v_mbcnt_hi_u32_b32 v106, -1, v106
	global_load_dwordx4 v[72:75], v56, s[24:25] nt
	global_load_dwordx4 v[76:79], v56, s[26:27] nt
	global_load_dwordx4 v[60:63], v56, s[24:25] offset:16 nt
	global_load_dwordx4 v[64:67], v56, s[26:27] offset:16 nt
	global_load_dwordx4 v[80:83], v56, s[22:23] nt
	global_load_dwordx4 v[68:71], v56, s[22:23] offset:16 nt
	global_load_dwordx4 v[84:87], v56, s[28:29] nt
	s_nop 0
	global_load_dwordx4 v[56:59], v56, s[28:29] offset:16 nt
	v_or_b32_e32 v105, s84, v99
	s_cmp_eq_u32 s84, 63
	v_lshlrev_b32_e32 v114, 1, v98
	v_lshlrev_b32_e32 v117, 4, v98
	v_cmp_ne_u32_e64 s[0:1], 0, v105
	s_cselect_b64 s[72:73], -1, 0
	s_or_b32 s4, s4, s85
	v_ashrrev_i32_e32 v107, 31, v106
	s_waitcnt vmcnt(22)
	v_lshlrev_b32_e32 v112, 16, v50
	v_and_b32_e32 v113, 0xffff0000, v50
	v_cndmask_b32_e64 v105, 0, v91, s[0:1]
	v_and_b32_e32 v50, 24, v114
	v_and_b32_e32 v114, 48, v117
	v_cndmask_b32_e64 v117, 0, v89, s[0:1]
	v_cndmask_b32_e64 v91, 0, v88, s[0:1]
	v_lshl_add_u64 v[88:89], s[4:5], 0, v[106:107]
	s_add_i32 s16, s16, s35
	v_lshlrev_b64 v[88:89], 7, v[88:89]
	s_mov_b32 s3, s17
	v_lshrrev_b32_e32 v115, 6, v100
	s_lshl_b32 s2, s16, 2
	v_lshl_add_u64 v[88:89], s[20:21], 0, v[88:89]
	v_cmp_eq_u32_e32 vcc, 31, v99
	v_lshlrev_b32_e32 v116, 8, v99
	v_add_u32_e32 v50, v50, v115
	v_lshl_add_u64 v[88:89], v[88:89], 0, s[2:3]
	v_lshlrev_b32_e32 v108, 16, v48
	v_and_b32_e32 v109, 0xffff0000, v48
	s_waitcnt vmcnt(21)
	v_lshlrev_b32_e32 v98, 16, v52
	v_and_b32_e32 v99, 0xffff0000, v52
	v_lshlrev_b32_e32 v110, 16, v49
	v_and_b32_e32 v111, 0xffff0000, v49
	v_lshlrev_b32_e32 v48, 16, v53
	v_and_b32_e32 v49, 0xffff0000, v53
	v_lshlrev_b32_e32 v52, 16, v54
	v_and_b32_e32 v53, 0xffff0000, v54
	v_and_b32_e32 v54, 0x300, v116
	v_cndmask_b32_e64 v116, 0, v90, s[0:1]
	s_and_b64 s[0:1], s[72:73], vcc
	v_lshl_add_u32 v50, v50, 10, 0
	v_lshlrev_b32_e32 v90, 16, v91
	v_and_b32_e32 v91, 0xffff0000, v91
	v_add_co_u32_e32 v106, vcc, s65, v88
	v_add3_u32 v124, v50, v54, v114
	s_nop 0
	v_addc_co_u32_e32 v107, vcc, 0, v89, vcc
	v_mov_b32_e32 v141, s2
	global_load_dword v141, v141, s[68:69] nt
	global_load_dword v50, v[88:89], off nt
	global_load_dword v54, v[106:107], off nt
	s_waitcnt vmcnt(20)
	v_cndmask_b32_e64 v120, v95, 0, s[0:1]
	v_cndmask_b32_e64 v121, v94, 0, s[0:1]
	v_cndmask_b32_e64 v122, v93, 0, s[0:1]
	v_cndmask_b32_e64 v123, v92, 0, s[0:1]
	v_lshlrev_b32_e32 v92, 16, v117
	v_and_b32_e32 v93, 0xffff0000, v117
	v_lshlrev_b32_e32 v94, 16, v116
	v_and_b32_e32 v95, 0xffff0000, v116
	v_lshlrev_b32_e32 v116, 16, v44
	v_and_b32_e32 v117, 0xffff0000, v44
	s_waitcnt vmcnt(8)
	v_pk_fma_f32 v[88:89], v[72:73], v[90:91], v[76:77]
	v_pk_fma_f32 v[90:91], v[74:75], v[92:93], v[78:79]
	s_waitcnt vmcnt(6)
	v_pk_fma_f32 v[92:93], v[60:61], v[94:95], v[64:65]
	s_waitcnt vmcnt(5)
	v_pk_fma_f32 v[88:89], v[80:81], v[108:109], v[88:89]
	v_pk_fma_f32 v[90:91], v[82:83], v[110:111], v[90:91]
	s_waitcnt vmcnt(3)
	v_pk_fma_f32 v[88:89], v[84:85], v[98:99], v[88:89]
	v_pk_fma_f32 v[92:93], v[68:69], v[112:113], v[92:93]
	v_mul_f32_e32 v94, 0xbfb8aa3b, v88
	v_mul_f32_e32 v95, 0xbfb8aa3b, v89
	v_exp_f32_e32 v94, v94
	v_exp_f32_e32 v95, v95
	v_pk_fma_f32 v[90:91], v[86:87], v[48:49], v[90:91]
	s_waitcnt vmcnt(2)
	v_pk_fma_f32 v[92:93], v[56:57], v[52:53], v[92:93]
	v_add_f32_e32 v94, 1.0, v94
	v_add_f32_e32 v95, 1.0, v95
	v_rcp_f32_e32 v94, v94
	v_rcp_f32_e32 v95, v95
	v_mul_f32_e32 v106, 0xbfb8aa3b, v90
	v_mul_f32_e32 v107, 0xbfb8aa3b, v91
	v_exp_f32_e32 v106, v106
	v_exp_f32_e32 v107, v107
	v_pk_mul_f32 v[88:89], v[88:89], v[94:95]
	v_mul_f32_e32 v94, 0xbfb8aa3b, v92
	v_mul_f32_e32 v95, 0xbfb8aa3b, v93
	v_exp_f32_e32 v94, v94
	v_exp_f32_e32 v95, v95
	v_add_f32_e32 v106, 1.0, v106
	v_add_f32_e32 v107, 1.0, v107
	v_rcp_f32_e32 v106, v106
	v_rcp_f32_e32 v107, v107
	v_add_f32_e32 v94, 1.0, v94
	v_add_f32_e32 v95, 1.0, v95
	v_rcp_f32_e32 v94, v94
	v_rcp_f32_e32 v95, v95
	v_pk_mul_f32 v[90:91], v[90:91], v[106:107]
	v_cvt_pk_bf16_f32 v88, v88, v89
	v_cvt_pk_bf16_f32 v89, v90, v91
	v_pk_mul_f32 v[90:91], v[92:93], v[94:95]
	v_lshlrev_b32_e32 v92, 16, v105
	v_and_b32_e32 v93, 0xffff0000, v105
	v_pk_fma_f32 v[92:93], v[62:63], v[92:93], v[66:67]
	v_lshlrev_b32_e32 v94, 16, v51
	v_and_b32_e32 v95, 0xffff0000, v51
	v_pk_fma_f32 v[92:93], v[70:71], v[94:95], v[92:93]
	v_lshlrev_b32_e32 v106, 16, v55
	v_and_b32_e32 v107, 0xffff0000, v55
	v_pk_fma_f32 v[92:93], v[58:59], v[106:107], v[92:93]
	v_pk_fma_f32 v[108:109], v[72:73], v[108:109], v[76:77]
	v_mul_f32_e32 v51, 0xbfb8aa3b, v92
	v_exp_f32_e32 v51, v51
	v_mul_f32_e32 v55, 0xbfb8aa3b, v93
	v_exp_f32_e32 v55, v55
	v_pk_fma_f32 v[108:109], v[80:81], v[98:99], v[108:109]
	v_add_f32_e32 v51, 1.0, v51
	v_rcp_f32_e32 v114, v51
	v_add_f32_e32 v51, 1.0, v55
	v_rcp_f32_e32 v115, v51
	v_pk_fma_f32 v[108:109], v[84:85], v[116:117], v[108:109]
	v_cvt_pk_bf16_f32 v90, v90, v91
	v_mul_f32_e32 v44, 0xbfb8aa3b, v108
	v_exp_f32_e32 v44, v44
	v_mul_f32_e32 v55, 0xbfb8aa3b, v109
	v_exp_f32_e32 v55, v55
	v_pk_mul_f32 v[92:93], v[92:93], v[114:115]
	v_add_f32_e32 v44, 1.0, v44
	v_cvt_pk_bf16_f32 v91, v92, v93
	ds_write_b128 v124, v[88:91]
	v_pk_fma_f32 v[90:91], v[74:75], v[110:111], v[78:79]
	v_lshlrev_b32_e32 v92, 16, v45
	v_pk_fma_f32 v[90:91], v[82:83], v[48:49], v[90:91]
	v_and_b32_e32 v93, 0xffff0000, v45
	v_rcp_f32_e32 v118, v44
	v_add_f32_e32 v44, 1.0, v55
	v_pk_fma_f32 v[90:91], v[86:87], v[92:93], v[90:91]
	v_rcp_f32_e32 v119, v44
	v_mul_f32_e32 v44, 0xbfb8aa3b, v90
	v_exp_f32_e32 v45, v44
	v_mul_f32_e32 v44, 0xbfb8aa3b, v91
; __device__ __forceinline__ unsigned cvtpk(float lo, float hi) { f32x2_t v = {lo, hi}; bf16x2_t b = __builtin_convertvector(v, bf16x2_t); return __builtin_bit_cast(unsigned, b); }
; __device__ __forceinline__ float lo16(unsigned u) { return __uint_as_float(u << 16); }
; __device__ __forceinline__ float hi16(unsigned u) { return __uint_as_float(u & 0xffff0000u); }
; __device__ __forceinline__ float silu_fast(float v) { return v * __builtin_amdgcn_rcpf(1.f + __builtin_amdgcn_exp2f(-v * LOG2E)); }
; __device__ __forceinline__ unsigned cvtpk(float lo, float hi) { f32x2_t v = {lo, hi}; bf16x2_t b = __builtin_convertvector(v, bf16x2_t); return __builtin_bit_cast(unsigned, b); }
; template <int NR, class Put>
; __device__ __forceinline__ void conv_compute_n(const ConvRawN<NR>& R, const float* cw, const float* cb, int col0, int rg, const Put& put) {
;     const f32x4 w0a = *(const f32x4*)(cw + col0), w0b = *(const f32x4*)(cw + col0 + 4), w1a = *(const f32x4*)(cw + XBCW + col0), w1b = *(const f32x4*)(cw + XBCW + col0 + 4);
;     const f32x4 w2a = *(const f32x4*)(cw + 2 * XBCW + col0), w2b = *(const f32x4*)(cw + 2 * XBCW + col0 + 4), ba = *(const f32x4*)(cb + col0), bb = *(const f32x4*)(cb + col0 + 4);
;     const int r0 = NR * rg;
; #pragma unroll
;     for (int rr = 0; rr < NR; ++rr) {
;         const u32x4 xm = R.r[rr], x0 = R.r[rr + 1], xp = R.r[rr + 2]; u32x4 o;
; #pragma unroll
;         for (int e = 0; e < 4; ++e) {
;             const float wl0 = e < 2 ? w0a[2 * e] : w0b[2 * e - 4], wh0 = e < 2 ? w0a[2 * e + 1] : w0b[2 * e - 3];
;             const float wl1 = e < 2 ? w1a[2 * e] : w1b[2 * e - 4], wh1 = e < 2 ? w1a[2 * e + 1] : w1b[2 * e - 3];
;             const float wl2 = e < 2 ? w2a[2 * e] : w2b[2 * e - 4], wh2 = e < 2 ? w2a[2 * e + 1] : w2b[2 * e - 3];
;             const float bl = e < 2 ? ba[2 * e] : bb[2 * e - 4], bh = e < 2 ? ba[2 * e + 1] : bb[2 * e - 3];
;             const float vl = bl + wl0 * lo16(xm[e]) + wl1 * lo16(x0[e]) + wl2 * lo16(xp[e]);
;             const float vh = bh + wh0 * hi16(xm[e]) + wh1 * hi16(x0[e]) + wh2 * hi16(xp[e]);
;             o[e] = cvtpk(silu_fast(vl), silu_fast(vh));
;         }
;         put(r0 + rr, o);
;     }
; }
; __device__ __forceinline__ void vec_compute(Frame& F, const Ptrs& P, int b, int c, int h0, float v0, float v1, float* DEC) {
;     ...
;     const float A2 = -expf(dir ? P.alb[h] : P.alf[h]) * LOG2E;
	v_exp_f32_e32 v51, v44
	v_pk_mul_f32 v[88:89], v[108:109], v[118:119]
	v_add_f32_e32 v45, 1.0, v45
	v_cvt_pk_bf16_f32 v44, v88, v89
	v_rcp_f32_e32 v88, v45
	v_add_f32_e32 v45, 1.0, v51
	v_pk_fma_f32 v[108:109], v[60:61], v[112:113], v[64:65]
	v_rcp_f32_e32 v89, v45
	v_pk_fma_f32 v[108:109], v[68:69], v[52:53], v[108:109]
	v_lshlrev_b32_e32 v110, 16, v46
	v_and_b32_e32 v111, 0xffff0000, v46
	v_pk_fma_f32 v[108:109], v[56:57], v[110:111], v[108:109]
	v_pk_mul_f32 v[88:89], v[90:91], v[88:89]
	v_mul_f32_e32 v45, 0xbfb8aa3b, v108
	v_exp_f32_e32 v45, v45
	v_mul_f32_e32 v46, 0xbfb8aa3b, v109
	v_exp_f32_e32 v51, v46
	v_pk_fma_f32 v[90:91], v[62:63], v[94:95], v[66:67]
	v_lshlrev_b32_e32 v94, 16, v47
	v_pk_fma_f32 v[90:91], v[70:71], v[106:107], v[90:91]
	v_and_b32_e32 v95, 0xffff0000, v47
	v_pk_fma_f32 v[90:91], v[58:59], v[94:95], v[90:91]
	v_add_f32_e32 v45, 1.0, v45
	v_mul_f32_e32 v47, 0xbfb8aa3b, v90
	v_rcp_f32_e32 v46, v45
	v_add_f32_e32 v45, 1.0, v51
	v_exp_f32_e32 v51, v47
	v_mul_f32_e32 v47, 0xbfb8aa3b, v91
	v_exp_f32_e32 v55, v47
	v_rcp_f32_e32 v47, v45
	v_add_f32_e32 v45, 1.0, v51
	v_rcp_f32_e32 v112, v45
	v_add_f32_e32 v45, 1.0, v55
	v_rcp_f32_e32 v113, v45
	v_cvt_pk_bf16_f32 v45, v88, v89
	v_pk_mul_f32 v[46:47], v[108:109], v[46:47]
	v_pk_fma_f32 v[52:53], v[60:61], v[52:53], v[64:65]
	v_pk_mul_f32 v[88:89], v[90:91], v[112:113]
	v_cvt_pk_bf16_f32 v46, v46, v47
	v_cvt_pk_bf16_f32 v47, v88, v89
	v_pk_fma_f32 v[88:89], v[72:73], v[98:99], v[76:77]
	v_lshlrev_b32_e32 v90, 16, v40
	v_pk_fma_f32 v[88:89], v[80:81], v[116:117], v[88:89]
	v_and_b32_e32 v91, 0xffff0000, v40
	v_pk_fma_f32 v[88:89], v[84:85], v[90:91], v[88:89]
	ds_write_b128 v124, v[44:47] offset:64
	v_mul_f32_e32 v40, 0xbfb8aa3b, v88
	v_exp_f32_e32 v40, v40
	v_mul_f32_e32 v51, 0xbfb8aa3b, v89
	v_exp_f32_e32 v51, v51
	v_pk_fma_f32 v[46:47], v[74:75], v[48:49], v[78:79]
	v_add_f32_e32 v40, 1.0, v40
	v_rcp_f32_e32 v44, v40
	v_add_f32_e32 v40, 1.0, v51
	v_rcp_f32_e32 v45, v40
	v_pk_fma_f32 v[46:47], v[82:83], v[92:93], v[46:47]
	v_lshlrev_b32_e32 v48, 16, v41
	v_and_b32_e32 v49, 0xffff0000, v41
	v_pk_fma_f32 v[46:47], v[86:87], v[48:49], v[46:47]
	v_pk_fma_f32 v[52:53], v[68:69], v[110:111], v[52:53]
	v_mul_f32_e32 v40, 0xbfb8aa3b, v46
	v_exp_f32_e32 v51, v40
	v_mul_f32_e32 v40, 0xbfb8aa3b, v47
	v_exp_f32_e32 v55, v40
	v_pk_mul_f32 v[40:41], v[88:89], v[44:45]
	v_lshlrev_b32_e32 v88, 16, v42
	v_and_b32_e32 v89, 0xffff0000, v42
	v_pk_fma_f32 v[52:53], v[56:57], v[88:89], v[52:53]
	v_add_f32_e32 v44, 1.0, v51
	v_mul_f32_e32 v42, 0xbfb8aa3b, v52
	v_exp_f32_e32 v42, v42
	v_mul_f32_e32 v51, 0xbfb8aa3b, v53
	v_exp_f32_e32 v51, v51
	v_add_f32_e32 v45, 1.0, v55
	v_add_f32_e32 v42, 1.0, v42
	v_rcp_f32_e32 v44, v44
	v_rcp_f32_e32 v45, v45
	v_rcp_f32_e32 v98, v42
	v_add_f32_e32 v42, 1.0, v51
	v_rcp_f32_e32 v99, v42
	v_pk_mul_f32 v[44:45], v[46:47], v[44:45]
	v_pk_fma_f32 v[46:47], v[62:63], v[106:107], v[66:67]
	v_cvt_pk_bf16_f32 v40, v40, v41
	v_cvt_pk_bf16_f32 v41, v44, v45
	v_pk_mul_f32 v[44:45], v[52:53], v[98:99]
	v_pk_fma_f32 v[46:47], v[70:71], v[94:95], v[46:47]
	v_lshlrev_b32_e32 v52, 16, v43
	v_and_b32_e32 v53, 0xffff0000, v43
	v_pk_fma_f32 v[46:47], v[58:59], v[52:53], v[46:47]
	v_pk_fma_f32 v[72:73], v[72:73], v[116:117], v[76:77]
	v_mul_f32_e32 v42, 0xbfb8aa3b, v46
	v_exp_f32_e32 v43, v42
	v_mul_f32_e32 v42, 0xbfb8aa3b, v47
	v_exp_f32_e32 v51, v42
	v_lshlrev_b32_e32 v98, 16, v123
	v_and_b32_e32 v99, 0xffff0000, v123
	v_pk_fma_f32 v[72:73], v[80:81], v[90:91], v[72:73]
	v_cvt_pk_bf16_f32 v42, v44, v45
	v_pk_fma_f32 v[72:73], v[84:85], v[98:99], v[72:73]
	v_add_f32_e32 v43, 1.0, v43
	v_mul_f32_e32 v45, 0xbfb8aa3b, v72
	v_rcp_f32_e32 v44, v43
	v_add_f32_e32 v43, 1.0, v51
	v_exp_f32_e32 v51, v45
	v_mul_f32_e32 v45, 0xbfb8aa3b, v73
	v_exp_f32_e32 v55, v45
	v_rcp_f32_e32 v45, v43
	v_add_f32_e32 v43, 1.0, v51
	v_rcp_f32_e32 v76, v43
	v_add_f32_e32 v43, 1.0, v55
	v_pk_mul_f32 v[44:45], v[46:47], v[44:45]
	v_rcp_f32_e32 v77, v43
	v_cvt_pk_bf16_f32 v43, v44, v45
	v_pk_fma_f32 v[44:45], v[74:75], v[92:93], v[78:79]
	ds_write_b128 v124, v[40:43] offset:128
	v_lshlrev_b32_e32 v42, 16, v122
	v_and_b32_e32 v43, 0xffff0000, v122
	v_pk_fma_f32 v[44:45], v[82:83], v[48:49], v[44:45]
	v_pk_mul_f32 v[40:41], v[72:73], v[76:77]
	v_pk_fma_f32 v[42:43], v[86:87], v[42:43], v[44:45]
	v_pk_fma_f32 v[48:49], v[60:61], v[110:111], v[64:65]
	v_mul_f32_e32 v44, 0xbfb8aa3b, v42
	v_exp_f32_e32 v44, v44
	v_mul_f32_e32 v45, 0xbfb8aa3b, v43
	v_exp_f32_e32 v45, v45
	v_cvt_pk_bf16_f32 v40, v40, v41
	v_add_f32_e32 v41, 1.0, v44
	v_lshlrev_b32_e32 v46, 16, v121
	v_and_b32_e32 v47, 0xffff0000, v121
	v_pk_fma_f32 v[48:49], v[68:69], v[88:89], v[48:49]
	v_rcp_f32_e32 v44, v41
	v_add_f32_e32 v41, 1.0, v45
	v_pk_fma_f32 v[46:47], v[56:57], v[46:47], v[48:49]
	v_rcp_f32_e32 v45, v41
	v_mul_f32_e32 v41, 0xbfb8aa3b, v46
	v_exp_f32_e32 v41, v41
	v_mul_f32_e32 v48, 0xbfb8aa3b, v47
	v_exp_f32_e32 v48, v48
	v_pk_mul_f32 v[42:43], v[42:43], v[44:45]
	v_add_f32_e32 v41, 1.0, v41
	v_rcp_f32_e32 v44, v41
	v_add_f32_e32 v41, 1.0, v48
	v_pk_fma_f32 v[48:49], v[62:63], v[94:95], v[66:67]
	s_nop 0
	v_pk_fma_f32 v[48:49], v[70:71], v[52:53], v[48:49]
	v_lshlrev_b32_e32 v52, 16, v120
	v_and_b32_e32 v53, 0xffff0000, v120
	v_pk_fma_f32 v[48:49], v[58:59], v[52:53], v[48:49]
	s_nop 0
	v_mul_f32_e32 v45, 0xbfb8aa3b, v48
	v_exp_f32_e32 v51, v45
	v_mul_f32_e32 v45, 0xbfb8aa3b, v49
	v_exp_f32_e32 v53, v45
	v_rcp_f32_e32 v45, v41
	v_add_f32_e32 v41, 1.0, v51
	v_rcp_f32_e32 v52, v41
	v_add_f32_e32 v41, 1.0, v53
	v_rcp_f32_e32 v53, v41
	v_cvt_pk_bf16_f32 v41, v42, v43
	v_pk_mul_f32 v[42:43], v[46:47], v[44:45]
	v_pk_mul_f32 v[44:45], v[48:49], v[52:53]
	v_cvt_pk_bf16_f32 v42, v42, v43
	v_cvt_pk_bf16_f32 v43, v44, v45
	ds_write_b128 v124, v[40:43] offset:192
	v_mov_b32_e32 v40, s2
	v_mbcnt_lo_u32_b32 v41, -1, 0
	v_mbcnt_hi_u32_b32 v41, -1, v41
	v_mov_b32_e32 v40, v141
	v_cmp_gt_i32_e64 s[0:1], 32, v41
	s_waitcnt vmcnt(0)
	v_mul_f32_e32 v42, 0x3fb8aa3b, v40
	v_fma_f32 v43, v40, s78, -v42
	v_rndne_f32_e32 v44, v42
	v_fmac_f32_e32 v43, 0x32a5705f, v40
	v_sub_f32_e32 v42, v42, v44
	v_add_f32_e32 v42, v42, v43
	v_exp_f32_e32 v42, v42
	v_cvt_i32_f32_e32 v43, v44
	v_cmp_ngt_f32_e32 vcc, s79, v40
	v_ldexp_f32 v42, v42, v43
	s_nop 0
	v_cndmask_b32_e32 v42, 0, v42, vcc
	v_cmp_nlt_f32_e32 vcc, s80, v40
	s_nop 1
	v_cndmask_b32_e32 v40, v134, v42, vcc
	v_mul_f32_e32 v40, 0xbfb8aa3b, v40
	s_and_b64 vcc, exec, s[62:63]
	s_cbranch_vccz .LBB0_573
; __device__ __forceinline__ float shfl_from(float x, int src_lane) { return __builtin_bit_cast(float, __builtin_amdgcn_ds_bpermute(src_lane << 2, __builtin_bit_cast(int, x))); }
; __device__ __forceinline__ float incl_suffix(float x, int lane) {
; #pragma unroll
;     for (int o = 1; o < 64; o <<= 1) { const float t = shfl_from(x, lane + o < 64 ? lane + o : lane); if (lane + o < 64) x += t; }
;     return x;
; }
; __device__ __forceinline__ void vec_compute(Frame& F, const Ptrs& P, int b, int c, int h0, float v0, float v1, float* DEC) {
;     ...
;     if (dir == 0) { const float p0 = incl_prefix(v0, lane), t0 = shfl_from(p0, 63), p1 = incl_prefix(v1, lane) + t0; a0 = A2 * p0; a1 = A2 * p1; aend = shfl_from(a1, 63); }
;     else { const float s1 = incl_suffix(v1, lane), t1 = shfl_from(s1, 0), s0 = incl_suffix(v0, lane) + t1; a0 = A2 * s0; a1 = A2 * s1; aend = shfl_from(a0, 0); }
	v_cmp_gt_i32_e32 vcc, 63, v41
	v_lshlrev_b32_e32 v44, 2, v41
	v_add_u32_e32 v45, 8, v44
	v_addc_co_u32_e64 v42, s[2:3], 0, v41, vcc
	v_lshlrev_b32_e32 v42, 2, v42
	ds_bpermute_b32 v43, v42, v54
	ds_bpermute_b32 v42, v42, v50
	v_cmp_gt_i32_e64 s[2:3], 62, v41
	v_add_u32_e32 v47, 16, v44
	v_cmp_gt_i32_e64 s[4:5], 60, v41
	s_waitcnt lgkmcnt(1)
	v_add_f32_e32 v43, v54, v43
	v_cndmask_b32_e32 v43, v54, v43, vcc
	v_cndmask_b32_e64 v45, v44, v45, s[2:3]
	s_waitcnt lgkmcnt(0)
	v_add_f32_e32 v42, v50, v42
	ds_bpermute_b32 v46, v45, v43
	v_cndmask_b32_e32 v42, v50, v42, vcc
	ds_bpermute_b32 v45, v45, v42
	v_add_u32_e32 v48, 32, v44
	v_cmp_gt_i32_e64 s[6:7], 56, v41
	s_waitcnt lgkmcnt(1)
	v_add_f32_e32 v46, v43, v46
	v_cndmask_b32_e64 v43, v43, v46, s[2:3]
	v_cndmask_b32_e64 v46, v44, v47, s[4:5]
	s_waitcnt lgkmcnt(0)
	v_add_f32_e32 v45, v42, v45
	ds_bpermute_b32 v47, v46, v43
	v_cndmask_b32_e64 v42, v42, v45, s[2:3]
	ds_bpermute_b32 v45, v46, v42
	v_add_u32_e32 v46, 64, v44
	v_cmp_gt_i32_e32 vcc, 48, v41
	s_waitcnt lgkmcnt(1)
	v_add_f32_e32 v47, v43, v47
	v_cndmask_b32_e64 v43, v43, v47, s[4:5]
	v_cndmask_b32_e64 v47, v44, v48, s[6:7]
	s_waitcnt lgkmcnt(0)
	v_add_f32_e32 v45, v42, v45
	ds_bpermute_b32 v48, v47, v43
	v_cndmask_b32_e64 v42, v42, v45, s[4:5]
	ds_bpermute_b32 v45, v47, v42
	v_cndmask_b32_e32 v46, v44, v46, vcc
	s_waitcnt lgkmcnt(1)
	v_add_f32_e32 v48, v43, v48
	v_cndmask_b32_e64 v43, v43, v48, s[6:7]
	s_waitcnt lgkmcnt(0)
	v_add_f32_e32 v45, v42, v45
	ds_bpermute_b32 v48, v46, v43
	v_cndmask_b32_e64 v42, v42, v45, s[6:7]
	ds_bpermute_b32 v45, v46, v42
	v_add_u32_e32 v46, 0x80, v44
	v_cndmask_b32_e64 v44, v44, v46, s[0:1]
	s_waitcnt lgkmcnt(1)
	v_add_f32_e32 v47, v43, v48
	v_cndmask_b32_e32 v43, v43, v47, vcc
	s_waitcnt lgkmcnt(0)
	v_add_f32_e32 v45, v42, v45
	ds_bpermute_b32 v46, v44, v43
	v_cndmask_b32_e32 v45, v42, v45, vcc
	ds_bpermute_b32 v44, v44, v45
	s_waitcnt lgkmcnt(1)
	v_add_f32_e32 v42, v43, v46
	v_cndmask_b32_e64 v42, v43, v42, s[0:1]
	s_waitcnt lgkmcnt(0)
	v_add_f32_e32 v43, v45, v44
	v_readlane_b32 s2, v42, 0
	v_cndmask_b32_e64 v43, v45, v43, s[0:1]
	s_nop 0
	v_add_f32_e32 v43, s2, v43
	v_pk_mul_f32 v[42:43], v[40:41], v[42:43] op_sel_hi:[0,1]
	s_nop 0
	v_readlane_b32 s2, v43, 0
	s_cbranch_execz .LBB0_574
	s_branch .LBB0_575

; __device__ __forceinline__ unsigned cvtpk(float lo, float hi) { f32x2_t v = {lo, hi}; bf16x2_t b = __builtin_convertvector(v, bf16x2_t); return __builtin_bit_cast(unsigned, b); }
; __device__ __forceinline__ float lo16(unsigned u) { return __uint_as_float(u << 16); }
; __device__ __forceinline__ float hi16(unsigned u) { return __uint_as_float(u & 0xffff0000u); }
; __device__ __forceinline__ void conv_load(ConvRaw& R, const bf16* XBC, int b, int c, int col0, int rg) {
;     const int r0 = 8 * rg;
; #pragma unroll
;     for (int i = 0; i < 10; ++i) { int t = c * 128 + r0 - 1 + i; t = t < 0 ? 0 : (t > SEQ - 1 ? SEQ - 1 : t); R.r[i] = *(const u32x4*)(XBC + ((size_t)b * SEQ + t) * XBCW + col0); }
;     if (c == 0 && rg == 0) R.r[0] = (u32x4){0u, 0u, 0u, 0u};
;     if (c == 63 && rg == 15) R.r[9] = (u32x4){0u, 0u, 0u, 0u};
; template <class Put>
; __device__ __forceinline__ void conv_compute(const ConvRaw& R, const float* cw, const float* cb, int col0, int rg, const Put& put) {
;     const f32x4 w0a = *(const f32x4*)(cw + col0), w0b = *(const f32x4*)(cw + col0 + 4), w1a = *(const f32x4*)(cw + XBCW + col0), w1b = *(const f32x4*)(cw + XBCW + col0 + 4);
;     const f32x4 w2a = *(const f32x4*)(cw + 2 * XBCW + col0), w2b = *(const f32x4*)(cw + 2 * XBCW + col0 + 4), ba = *(const f32x4*)(cb + col0), bb = *(const f32x4*)(cb + col0 + 4);
;     const int r0 = 8 * rg;
; #pragma unroll
;     for (int rr = 0; rr < 8; ++rr) {
;         const u32x4 xm = R.r[rr], x0 = R.r[rr + 1], xp = R.r[rr + 2]; u32x4 o;
; #pragma unroll
;         for (int e = 0; e < 4; ++e) {
;             const float wl0 = e < 2 ? w0a[2 * e] : w0b[2 * e - 4], wh0 = e < 2 ? w0a[2 * e + 1] : w0b[2 * e - 3];
;             const float wl1 = e < 2 ? w1a[2 * e] : w1b[2 * e - 4], wh1 = e < 2 ? w1a[2 * e + 1] : w1b[2 * e - 3];
;             const float wl2 = e < 2 ? w2a[2 * e] : w2b[2 * e - 4], wh2 = e < 2 ? w2a[2 * e + 1] : w2b[2 * e - 3];
;             const float bl = e < 2 ? ba[2 * e] : bb[2 * e - 4], bh = e < 2 ? ba[2 * e + 1] : bb[2 * e - 3];
;             const float vl = bl + wl0 * lo16(xm[e]) + wl1 * lo16(x0[e]) + wl2 * lo16(xp[e]);
;             const float vh = bh + wh0 * hi16(xm[e]) + wh1 * hi16(x0[e]) + wh2 * hi16(xp[e]);
;             o[e] = cvtpk(silu_fast(vl), silu_fast(vh));
;         }
;         put(r0 + rr, o);
;     }
; }
.LBB0_577:
	s_or_b64 exec, exec, s[0:1]
	v_lshlrev_b64 v[44:45], 2, v[96:97]
	v_lshl_add_u64 v[46:47], s[24:25], 0, v[44:45]
	global_load_dwordx4 v[40:43], v[46:47], off offset:16 nt
	global_load_dwordx4 v[56:59], v[46:47], off nt
	v_lshl_add_u64 v[46:47], s[26:27], 0, v[44:45]
	global_load_dwordx4 v[60:63], v[46:47], off nt
	global_load_dwordx4 v[48:51], v[46:47], off offset:16 nt
	v_lshl_add_u64 v[46:47], s[22:23], 0, v[44:45]
	global_load_dwordx4 v[64:67], v[46:47], off nt
	global_load_dwordx4 v[52:55], v[46:47], off offset:16 nt
	v_lshl_add_u64 v[44:45], s[28:29], 0, v[44:45]
	global_load_dwordx4 v[68:71], v[44:45], off nt
	s_nop 0
	global_load_dwordx4 v[44:47], v[44:45], off offset:16 nt
	global_load_dwordx4 v[188:191], v[146:147], off nt
	global_load_dwordx4 v[192:195], v[148:149], off nt
	global_load_dwordx4 v[196:199], v[150:151], off nt
	global_load_dwordx4 v[200:203], v[152:153], off nt
	global_load_dwordx4 v[204:207], v[154:155], off nt
	global_load_dwordx4 v[208:211], v[156:157], off nt
	global_load_dwordx4 v[212:215], v[158:159], off nt
	global_load_dwordx4 v[216:219], v[160:161], off nt
	global_load_dwordx4 v[220:223], v[162:163], off nt
	global_load_dwordx4 v[224:227], v[164:165], off nt
	global_load_dwordx4 v[228:231], v[166:167], off nt
	global_load_dwordx4 v[232:235], v[168:169], off nt
	global_load_dwordx4 v[236:239], v[170:171], off nt
	global_load_dwordx4 v[240:243], v[172:173], off nt
	global_load_dwordx4 v[244:247], v[174:175], off nt
	global_load_dwordx4 v[248:251], v[176:177], off nt
	v_or_b32_e32 v80, s84, v102
	v_cmp_eq_u32_e32 vcc, 15, v102
	v_lshlrev_b32_e32 v82, 1, v101
	v_lshrrev_b32_e32 v83, 1, v102
	v_cmp_ne_u32_e64 s[0:1], 0, v80
	v_lshlrev_b32_e32 v74, 16, v24
	v_and_b32_e32 v75, 0xffff0000, v24
	v_lshlrev_b32_e32 v72, 16, v28
	v_and_b32_e32 v73, 0xffff0000, v28
	v_lshlrev_b32_e32 v76, 16, v25
	v_and_b32_e32 v77, 0xffff0000, v25
	v_lshlrev_b32_e32 v24, 16, v29
	v_and_b32_e32 v25, 0xffff0000, v29
	v_lshlrev_b32_e32 v28, 16, v30
	v_and_b32_e32 v29, 0xffff0000, v30
	v_cndmask_b32_e64 v30, 0, v35, s[0:1]
	s_and_b64 s[4:5], s[72:73], vcc
	v_and_or_b32 v35, v82, 8, v83
	v_lshlrev_b32_e32 v81, 14, v103
	v_lshlrev_b32_e32 v78, 16, v26
	v_and_b32_e32 v79, 0xffff0000, v26
	v_cndmask_b32_e64 v26, v39, 0, s[4:5]
	v_cndmask_b32_e64 v83, 0, v34, s[0:1]
	v_cndmask_b32_e64 v82, 0, v33, s[0:1]
	v_cndmask_b32_e64 v39, 0, v32, s[0:1]
	v_lshlrev_b32_e32 v35, 10, v35
	v_cndmask_b32_e64 v32, v38, 0, s[4:5]
	v_cndmask_b32_e64 v33, v37, 0, s[4:5]
	v_cndmask_b32_e64 v34, v36, 0, s[4:5]
	v_lshlrev_b32_e32 v36, 16, v30
	v_and_b32_e32 v37, 0xffff0000, v30
	v_add3_u32 v30, s82, v81, v35
	v_lshlrev_b32_e32 v38, 16, v39
	v_and_b32_e32 v39, 0xffff0000, v39
	v_lshlrev_b32_e32 v80, 16, v82
	v_and_b32_e32 v81, 0xffff0000, v82
	v_lshlrev_b32_e32 v82, 16, v83
	v_and_b32_e32 v83, 0xffff0000, v83
	v_lshlrev_b32_e32 v84, 9, v102
	v_lshlrev_b32_e32 v85, 4, v101
	v_and_b32_e32 v84, 0x200, v84
	v_and_b32_e32 v85, 48, v85
	v_add3_u32 v30, v30, v84, v85
	v_lshrrev_b32_e32 v128, 5, v104
	v_lshlrev_b32_e32 v141, 4, v100
	s_mov_b32 s2, 0
	v_lshl_add_u32 v142, v128, 4, 0
	s_waitcnt vmcnt(21)
	v_pk_fma_f32 v[38:39], v[56:57], v[38:39], v[60:61]
	v_pk_fma_f32 v[80:81], v[58:59], v[80:81], v[62:63]
	s_waitcnt vmcnt(20)
	v_pk_fma_f32 v[82:83], v[40:41], v[82:83], v[48:49]
	s_waitcnt vmcnt(19)
	v_pk_fma_f32 v[38:39], v[64:65], v[74:75], v[38:39]
	v_pk_fma_f32 v[80:81], v[66:67], v[76:77], v[80:81]
	s_waitcnt vmcnt(18)
	v_pk_fma_f32 v[82:83], v[52:53], v[78:79], v[82:83]
	s_waitcnt vmcnt(17)
	v_pk_fma_f32 v[38:39], v[68:69], v[72:73], v[38:39]
	v_pk_fma_f32 v[80:81], v[70:71], v[24:25], v[80:81]
	s_waitcnt vmcnt(16)
	v_pk_fma_f32 v[82:83], v[44:45], v[28:29], v[82:83]
	v_mul_f32_e32 v35, 0xbfb8aa3b, v38
	v_mul_f32_e32 v84, 0xbfb8aa3b, v39
	v_mul_f32_e32 v85, 0xbfb8aa3b, v80
	v_mul_f32_e32 v86, 0xbfb8aa3b, v81
	v_mul_f32_e32 v87, 0xbfb8aa3b, v82
	v_mul_f32_e32 v88, 0xbfb8aa3b, v83
	v_exp_f32_e32 v35, v35
	v_exp_f32_e32 v84, v84
	v_exp_f32_e32 v85, v85
	v_exp_f32_e32 v86, v86
	v_exp_f32_e32 v87, v87
	v_exp_f32_e32 v88, v88
	v_add_f32_e32 v35, 1.0, v35
	v_add_f32_e32 v89, 1.0, v84
	v_add_f32_e32 v90, 1.0, v85
	v_add_f32_e32 v91, 1.0, v86
	v_add_f32_e32 v92, 1.0, v87
	v_add_f32_e32 v93, 1.0, v88
	v_rcp_f32_e32 v84, v35
	v_rcp_f32_e32 v85, v89
	v_rcp_f32_e32 v86, v90
	v_rcp_f32_e32 v87, v91
	v_rcp_f32_e32 v88, v92
	v_rcp_f32_e32 v89, v93
	v_pk_fma_f32 v[90:91], v[42:43], v[36:37], v[50:51]
	v_pk_mul_f32 v[36:37], v[38:39], v[84:85]
	v_pk_mul_f32 v[38:39], v[80:81], v[86:87]
	v_pk_mul_f32 v[80:81], v[82:83], v[88:89]
	v_lshlrev_b32_e32 v82, 16, v27
	v_and_b32_e32 v83, 0xffff0000, v27
	v_cvt_pk_bf16_f32 v36, v36, v37
	v_cvt_pk_bf16_f32 v37, v38, v39
	v_pk_fma_f32 v[38:39], v[54:55], v[82:83], v[90:91]
	v_lshlrev_b32_e32 v84, 16, v31
	v_and_b32_e32 v85, 0xffff0000, v31
	v_pk_fma_f32 v[86:87], v[46:47], v[84:85], v[38:39]
	v_pk_fma_f32 v[74:75], v[56:57], v[74:75], v[60:61]
	v_mul_f32_e32 v27, 0xbfb8aa3b, v86
	v_exp_f32_e32 v27, v27
	v_mul_f32_e32 v31, 0xbfb8aa3b, v87
	v_exp_f32_e32 v31, v31
	v_pk_fma_f32 v[74:75], v[64:65], v[72:73], v[74:75]
	v_lshlrev_b32_e32 v88, 16, v20
	v_and_b32_e32 v89, 0xffff0000, v20
	v_pk_fma_f32 v[74:75], v[68:69], v[88:89], v[74:75]
	v_add_f32_e32 v27, 1.0, v27
	v_mul_f32_e32 v20, 0xbfb8aa3b, v74
	v_cvt_pk_bf16_f32 v38, v80, v81
	v_rcp_f32_e32 v80, v27
	v_add_f32_e32 v27, 1.0, v31
	v_exp_f32_e32 v20, v20
	v_mul_f32_e32 v31, 0xbfb8aa3b, v75
	v_exp_f32_e32 v31, v31
	v_rcp_f32_e32 v81, v27
	v_add_f32_e32 v20, 1.0, v20
	v_rcp_f32_e32 v90, v20
	v_add_f32_e32 v20, 1.0, v31
	v_rcp_f32_e32 v91, v20
	v_pk_mul_f32 v[80:81], v[86:87], v[80:81]
; __device__ __forceinline__ unsigned cvtpk(float lo, float hi) { f32x2_t v = {lo, hi}; bf16x2_t b = __builtin_convertvector(v, bf16x2_t); return __builtin_bit_cast(unsigned, b); }
; __device__ __forceinline__ float lo16(unsigned u) { return __uint_as_float(u << 16); }
; __device__ __forceinline__ float hi16(unsigned u) { return __uint_as_float(u & 0xffff0000u); }
; __device__ __forceinline__ float silu_fast(float v) { return v * __builtin_amdgcn_rcpf(1.f + __builtin_amdgcn_exp2f(-v * LOG2E)); }
; __device__ __forceinline__ unsigned cvtpk(float lo, float hi) { f32x2_t v = {lo, hi}; bf16x2_t b = __builtin_convertvector(v, bf16x2_t); return __builtin_bit_cast(unsigned, b); }
; __device__ __forceinline__ float lo16(unsigned u) { return __uint_as_float(u << 16); }
; __device__ __forceinline__ float hi16(unsigned u) { return __uint_as_float(u & 0xffff0000u); }
; template <class Put>
; __device__ __forceinline__ void conv_compute(const ConvRaw& R, const float* cw, const float* cb, int col0, int rg, const Put& put) {
;     const f32x4 w0a = *(const f32x4*)(cw + col0), w0b = *(const f32x4*)(cw + col0 + 4), w1a = *(const f32x4*)(cw + XBCW + col0), w1b = *(const f32x4*)(cw + XBCW + col0 + 4);
;     const f32x4 w2a = *(const f32x4*)(cw + 2 * XBCW + col0), w2b = *(const f32x4*)(cw + 2 * XBCW + col0 + 4), ba = *(const f32x4*)(cb + col0), bb = *(const f32x4*)(cb + col0 + 4);
;     const int r0 = 8 * rg;
; #pragma unroll
;     for (int rr = 0; rr < 8; ++rr) {
;         const u32x4 xm = R.r[rr], x0 = R.r[rr + 1], xp = R.r[rr + 2]; u32x4 o;
; #pragma unroll
;         for (int e = 0; e < 4; ++e) {
;             const float wl0 = e < 2 ? w0a[2 * e] : w0b[2 * e - 4], wh0 = e < 2 ? w0a[2 * e + 1] : w0b[2 * e - 3];
;             const float wl1 = e < 2 ? w1a[2 * e] : w1b[2 * e - 4], wh1 = e < 2 ? w1a[2 * e + 1] : w1b[2 * e - 3];
;             const float wl2 = e < 2 ? w2a[2 * e] : w2b[2 * e - 4], wh2 = e < 2 ? w2a[2 * e + 1] : w2b[2 * e - 3];
;             const float bl = e < 2 ? ba[2 * e] : bb[2 * e - 4], bh = e < 2 ? ba[2 * e + 1] : bb[2 * e - 3];
;             const float vl = bl + wl0 * lo16(xm[e]) + wl1 * lo16(x0[e]) + wl2 * lo16(xp[e]);
;             const float vh = bh + wh0 * hi16(xm[e]) + wh1 * hi16(x0[e]) + wh2 * hi16(xp[e]);
;             o[e] = cvtpk(silu_fast(vl), silu_fast(vh));
;         }
;         put(r0 + rr, o);
;     }
; }
	s_nop 0
	v_cvt_pk_bf16_f32 v39, v80, v81
	ds_write_b128 v30, v[36:39]
	v_pk_fma_f32 v[38:39], v[58:59], v[76:77], v[62:63]
	v_pk_mul_f32 v[36:37], v[74:75], v[90:91]
	v_pk_fma_f32 v[38:39], v[66:67], v[24:25], v[38:39]
	v_lshlrev_b32_e32 v74, 16, v21
	v_and_b32_e32 v75, 0xffff0000, v21
	v_pk_fma_f32 v[38:39], v[70:71], v[74:75], v[38:39]
	v_pk_fma_f32 v[76:77], v[40:41], v[78:79], v[48:49]
	v_mul_f32_e32 v20, 0xbfb8aa3b, v38
	v_exp_f32_e32 v21, v20
	v_mul_f32_e32 v20, 0xbfb8aa3b, v39
	v_exp_f32_e32 v27, v20
	v_cvt_pk_bf16_f32 v20, v36, v37
	v_add_f32_e32 v21, 1.0, v21
	v_rcp_f32_e32 v36, v21
	v_add_f32_e32 v21, 1.0, v27
	v_rcp_f32_e32 v37, v21
	v_pk_fma_f32 v[76:77], v[52:53], v[28:29], v[76:77]
	v_lshlrev_b32_e32 v78, 16, v22
	v_and_b32_e32 v79, 0xffff0000, v22
	v_pk_fma_f32 v[76:77], v[44:45], v[78:79], v[76:77]
	v_pk_mul_f32 v[36:37], v[38:39], v[36:37]
	v_mul_f32_e32 v21, 0xbfb8aa3b, v76
	v_exp_f32_e32 v21, v21
	v_mul_f32_e32 v22, 0xbfb8aa3b, v77
	v_exp_f32_e32 v27, v22
	v_pk_fma_f32 v[38:39], v[42:43], v[82:83], v[50:51]
	v_lshlrev_b32_e32 v80, 16, v23
	v_pk_fma_f32 v[38:39], v[54:55], v[84:85], v[38:39]
	v_and_b32_e32 v81, 0xffff0000, v23
	v_pk_fma_f32 v[38:39], v[46:47], v[80:81], v[38:39]
	v_add_f32_e32 v21, 1.0, v21
	v_mul_f32_e32 v23, 0xbfb8aa3b, v38
	v_rcp_f32_e32 v22, v21
	v_add_f32_e32 v21, 1.0, v27
	v_exp_f32_e32 v27, v23
	v_mul_f32_e32 v23, 0xbfb8aa3b, v39
	v_exp_f32_e32 v31, v23
	v_rcp_f32_e32 v23, v21
	v_add_f32_e32 v21, 1.0, v27
	v_rcp_f32_e32 v82, v21
	v_add_f32_e32 v21, 1.0, v31
	v_rcp_f32_e32 v83, v21
	v_cvt_pk_bf16_f32 v21, v36, v37
	v_pk_mul_f32 v[22:23], v[76:77], v[22:23]
	v_pk_fma_f32 v[28:29], v[40:41], v[28:29], v[48:49]
	v_pk_mul_f32 v[36:37], v[38:39], v[82:83]
	v_cvt_pk_bf16_f32 v22, v22, v23
	v_cvt_pk_bf16_f32 v23, v36, v37
	v_pk_fma_f32 v[36:37], v[56:57], v[72:73], v[60:61]
	v_lshlrev_b32_e32 v38, 16, v16
	v_pk_fma_f32 v[36:37], v[64:65], v[88:89], v[36:37]
	v_and_b32_e32 v39, 0xffff0000, v16
	v_pk_fma_f32 v[36:37], v[68:69], v[38:39], v[36:37]
	ds_write_b128 v30, v[20:23] offset:64
	v_mul_f32_e32 v16, 0xbfb8aa3b, v36
	v_exp_f32_e32 v16, v16
	v_mul_f32_e32 v27, 0xbfb8aa3b, v37
	v_exp_f32_e32 v27, v27
	v_pk_fma_f32 v[22:23], v[58:59], v[24:25], v[62:63]
	v_add_f32_e32 v16, 1.0, v16
	v_rcp_f32_e32 v20, v16
	v_add_f32_e32 v16, 1.0, v27
	v_rcp_f32_e32 v21, v16
	v_pk_fma_f32 v[22:23], v[66:67], v[74:75], v[22:23]
	v_lshlrev_b32_e32 v24, 16, v17
	v_and_b32_e32 v25, 0xffff0000, v17
	v_pk_fma_f32 v[22:23], v[70:71], v[24:25], v[22:23]
	v_pk_fma_f32 v[28:29], v[52:53], v[78:79], v[28:29]
	v_mul_f32_e32 v16, 0xbfb8aa3b, v22
	v_exp_f32_e32 v27, v16
	v_mul_f32_e32 v16, 0xbfb8aa3b, v23
	v_exp_f32_e32 v31, v16
	v_pk_mul_f32 v[16:17], v[36:37], v[20:21]
	v_lshlrev_b32_e32 v36, 16, v18
	v_and_b32_e32 v37, 0xffff0000, v18
	v_pk_fma_f32 v[28:29], v[44:45], v[36:37], v[28:29]
	v_add_f32_e32 v20, 1.0, v27
	v_mul_f32_e32 v18, 0xbfb8aa3b, v28
	v_exp_f32_e32 v18, v18
	v_mul_f32_e32 v27, 0xbfb8aa3b, v29
	v_exp_f32_e32 v27, v27
	v_add_f32_e32 v21, 1.0, v31
	v_add_f32_e32 v18, 1.0, v18
	v_rcp_f32_e32 v20, v20
	v_rcp_f32_e32 v21, v21
	v_rcp_f32_e32 v72, v18
	v_add_f32_e32 v18, 1.0, v27
	v_rcp_f32_e32 v73, v18
	v_pk_mul_f32 v[20:21], v[22:23], v[20:21]
	v_pk_fma_f32 v[22:23], v[42:43], v[84:85], v[50:51]
	v_cvt_pk_bf16_f32 v16, v16, v17
	v_cvt_pk_bf16_f32 v17, v20, v21
	v_pk_mul_f32 v[20:21], v[28:29], v[72:73]
	v_pk_fma_f32 v[22:23], v[54:55], v[80:81], v[22:23]
	v_lshlrev_b32_e32 v28, 16, v19
	v_and_b32_e32 v29, 0xffff0000, v19
	v_pk_fma_f32 v[22:23], v[46:47], v[28:29], v[22:23]
	v_pk_fma_f32 v[72:73], v[56:57], v[88:89], v[60:61]
	v_mul_f32_e32 v18, 0xbfb8aa3b, v22
	v_exp_f32_e32 v19, v18
	v_mul_f32_e32 v18, 0xbfb8aa3b, v23
	v_exp_f32_e32 v27, v18
	v_pk_fma_f32 v[72:73], v[64:65], v[38:39], v[72:73]
	v_lshlrev_b32_e32 v76, 16, v12
	v_and_b32_e32 v77, 0xffff0000, v12
	v_add_f32_e32 v19, 1.0, v19
	v_pk_fma_f32 v[72:73], v[68:69], v[76:77], v[72:73]
	v_cvt_pk_bf16_f32 v18, v20, v21
	v_rcp_f32_e32 v20, v19
	v_add_f32_e32 v19, 1.0, v27
	v_mul_f32_e32 v21, 0xbfb8aa3b, v73
	v_exp_f32_e32 v27, v21
	v_rcp_f32_e32 v21, v19
	v_mul_f32_e32 v12, 0xbfb8aa3b, v72
	v_exp_f32_e32 v12, v12
	v_pk_mul_f32 v[20:21], v[22:23], v[20:21]
	s_nop 0
	v_cvt_pk_bf16_f32 v19, v20, v21
	ds_write_b128 v30, v[16:19] offset:128
	v_pk_fma_f32 v[18:19], v[58:59], v[74:75], v[62:63]
	v_add_f32_e32 v12, 1.0, v12
	v_pk_fma_f32 v[18:19], v[66:67], v[24:25], v[18:19]
	v_lshlrev_b32_e32 v20, 16, v13
	v_and_b32_e32 v21, 0xffff0000, v13
	v_rcp_f32_e32 v82, v12
	v_add_f32_e32 v12, 1.0, v27
	v_pk_fma_f32 v[18:19], v[70:71], v[20:21], v[18:19]
	v_rcp_f32_e32 v83, v12
	v_mul_f32_e32 v12, 0xbfb8aa3b, v18
	v_exp_f32_e32 v13, v12
	v_mul_f32_e32 v12, 0xbfb8aa3b, v19
	v_exp_f32_e32 v22, v12
	v_pk_mul_f32 v[16:17], v[72:73], v[82:83]
	v_add_f32_e32 v13, 1.0, v13
	v_cvt_pk_bf16_f32 v12, v16, v17
	v_rcp_f32_e32 v16, v13
	v_add_f32_e32 v13, 1.0, v22
	v_pk_fma_f32 v[22:23], v[40:41], v[78:79], v[48:49]
	v_rcp_f32_e32 v17, v13
	v_pk_fma_f32 v[22:23], v[52:53], v[36:37], v[22:23]
	v_lshlrev_b32_e32 v72, 16, v14
	v_and_b32_e32 v73, 0xffff0000, v14
	v_pk_fma_f32 v[22:23], v[44:45], v[72:73], v[22:23]
	v_pk_mul_f32 v[16:17], v[18:19], v[16:17]
	v_mul_f32_e32 v13, 0xbfb8aa3b, v22
	v_exp_f32_e32 v13, v13
	v_mul_f32_e32 v14, 0xbfb8aa3b, v23
	v_exp_f32_e32 v27, v14
	v_pk_fma_f32 v[18:19], v[42:43], v[80:81], v[50:51]
	v_lshlrev_b32_e32 v74, 16, v15
	v_pk_fma_f32 v[18:19], v[54:55], v[28:29], v[18:19]
	v_and_b32_e32 v75, 0xffff0000, v15
	v_pk_fma_f32 v[18:19], v[46:47], v[74:75], v[18:19]
	v_add_f32_e32 v13, 1.0, v13
	v_mul_f32_e32 v15, 0xbfb8aa3b, v18
	v_rcp_f32_e32 v14, v13
; __device__ __forceinline__ unsigned cvtpk(float lo, float hi) { f32x2_t v = {lo, hi}; bf16x2_t b = __builtin_convertvector(v, bf16x2_t); return __builtin_bit_cast(unsigned, b); }
; __device__ __forceinline__ float lo16(unsigned u) { return __uint_as_float(u << 16); }
; __device__ __forceinline__ float hi16(unsigned u) { return __uint_as_float(u & 0xffff0000u); }
; __device__ __forceinline__ float silu_fast(float v) { return v * __builtin_amdgcn_rcpf(1.f + __builtin_amdgcn_exp2f(-v * LOG2E)); }
; __device__ __forceinline__ unsigned cvtpk(float lo, float hi) { f32x2_t v = {lo, hi}; bf16x2_t b = __builtin_convertvector(v, bf16x2_t); return __builtin_bit_cast(unsigned, b); }
; __device__ __forceinline__ float lo16(unsigned u) { return __uint_as_float(u << 16); }
; __device__ __forceinline__ float hi16(unsigned u) { return __uint_as_float(u & 0xffff0000u); }
; template <class Put>
; __device__ __forceinline__ void conv_compute(const ConvRaw& R, const float* cw, const float* cb, int col0, int rg, const Put& put) {
;     const f32x4 w0a = *(const f32x4*)(cw + col0), w0b = *(const f32x4*)(cw + col0 + 4), w1a = *(const f32x4*)(cw + XBCW + col0), w1b = *(const f32x4*)(cw + XBCW + col0 + 4);
;     const f32x4 w2a = *(const f32x4*)(cw + 2 * XBCW + col0), w2b = *(const f32x4*)(cw + 2 * XBCW + col0 + 4), ba = *(const f32x4*)(cb + col0), bb = *(const f32x4*)(cb + col0 + 4);
;     const int r0 = 8 * rg;
; #pragma unroll
;     for (int rr = 0; rr < 8; ++rr) {
;         const u32x4 xm = R.r[rr], x0 = R.r[rr + 1], xp = R.r[rr + 2]; u32x4 o;
; #pragma unroll
;         for (int e = 0; e < 4; ++e) {
;             const float wl0 = e < 2 ? w0a[2 * e] : w0b[2 * e - 4], wh0 = e < 2 ? w0a[2 * e + 1] : w0b[2 * e - 3];
;             const float wl1 = e < 2 ? w1a[2 * e] : w1b[2 * e - 4], wh1 = e < 2 ? w1a[2 * e + 1] : w1b[2 * e - 3];
;             const float wl2 = e < 2 ? w2a[2 * e] : w2b[2 * e - 4], wh2 = e < 2 ? w2a[2 * e + 1] : w2b[2 * e - 3];
;             const float bl = e < 2 ? ba[2 * e] : bb[2 * e - 4], bh = e < 2 ? ba[2 * e + 1] : bb[2 * e - 3];
;             const float vl = bl + wl0 * lo16(xm[e]) + wl1 * lo16(x0[e]) + wl2 * lo16(xp[e]);
;             const float vh = bh + wh0 * hi16(xm[e]) + wh1 * hi16(x0[e]) + wh2 * hi16(xp[e]);
;             o[e] = cvtpk(silu_fast(vl), silu_fast(vh));
;         }
;         put(r0 + rr, o);
;     }
; }
	v_add_f32_e32 v13, 1.0, v27
	v_exp_f32_e32 v27, v15
	v_mul_f32_e32 v15, 0xbfb8aa3b, v19
	v_exp_f32_e32 v31, v15
	v_rcp_f32_e32 v15, v13
	v_add_f32_e32 v13, 1.0, v27
	v_rcp_f32_e32 v78, v13
	v_add_f32_e32 v13, 1.0, v31
	v_rcp_f32_e32 v79, v13
	v_cvt_pk_bf16_f32 v13, v16, v17
	v_pk_mul_f32 v[14:15], v[22:23], v[14:15]
	v_and_b32_e32 v23, 0xffff0000, v9
	v_pk_mul_f32 v[16:17], v[18:19], v[78:79]
	v_cvt_pk_bf16_f32 v14, v14, v15
	v_cvt_pk_bf16_f32 v15, v16, v17
	v_pk_fma_f32 v[16:17], v[56:57], v[38:39], v[60:61]
	v_lshlrev_b32_e32 v18, 16, v8
	v_pk_fma_f32 v[16:17], v[64:65], v[76:77], v[16:17]
	v_and_b32_e32 v19, 0xffff0000, v8
	v_pk_fma_f32 v[16:17], v[68:69], v[18:19], v[16:17]
	ds_write_b128 v30, v[12:15] offset:192
	v_mul_f32_e32 v8, 0xbfb8aa3b, v16
	v_exp_f32_e32 v8, v8
	v_mul_f32_e32 v22, 0xbfb8aa3b, v17
	v_exp_f32_e32 v22, v22
	v_pk_fma_f32 v[14:15], v[58:59], v[24:25], v[62:63]
	v_add_f32_e32 v8, 1.0, v8
	v_rcp_f32_e32 v12, v8
	v_add_f32_e32 v8, 1.0, v22
	v_pk_fma_f32 v[14:15], v[66:67], v[20:21], v[14:15]
	v_lshlrev_b32_e32 v22, 16, v9
	v_pk_fma_f32 v[14:15], v[70:71], v[22:23], v[14:15]
	v_rcp_f32_e32 v13, v8
	v_mul_f32_e32 v8, 0xbfb8aa3b, v14
	v_exp_f32_e32 v24, v8
	v_mul_f32_e32 v8, 0xbfb8aa3b, v15
	v_exp_f32_e32 v25, v8
	v_pk_mul_f32 v[8:9], v[16:17], v[12:13]
	v_pk_fma_f32 v[16:17], v[40:41], v[36:37], v[48:49]
	v_add_f32_e32 v12, 1.0, v24
	v_add_f32_e32 v13, 1.0, v25
	v_pk_fma_f32 v[16:17], v[52:53], v[72:73], v[16:17]
	v_lshlrev_b32_e32 v24, 16, v10
	v_and_b32_e32 v25, 0xffff0000, v10
	v_pk_fma_f32 v[16:17], v[44:45], v[24:25], v[16:17]
	v_rcp_f32_e32 v12, v12
	v_mul_f32_e32 v10, 0xbfb8aa3b, v16
	v_exp_f32_e32 v10, v10
	v_mul_f32_e32 v27, 0xbfb8aa3b, v17
	v_exp_f32_e32 v27, v27
	v_rcp_f32_e32 v13, v13
	v_add_f32_e32 v10, 1.0, v10
	v_rcp_f32_e32 v36, v10
	v_add_f32_e32 v10, 1.0, v27
	v_rcp_f32_e32 v37, v10
	v_pk_mul_f32 v[12:13], v[14:15], v[12:13]
	v_pk_fma_f32 v[14:15], v[42:43], v[28:29], v[50:51]
	v_cvt_pk_bf16_f32 v8, v8, v9
	v_cvt_pk_bf16_f32 v9, v12, v13
	v_pk_mul_f32 v[12:13], v[16:17], v[36:37]
	v_pk_fma_f32 v[14:15], v[54:55], v[74:75], v[14:15]
	v_lshlrev_b32_e32 v16, 16, v11
	v_and_b32_e32 v17, 0xffff0000, v11
	v_pk_fma_f32 v[14:15], v[46:47], v[16:17], v[14:15]
	v_pk_fma_f32 v[28:29], v[56:57], v[76:77], v[60:61]
	v_mul_f32_e32 v10, 0xbfb8aa3b, v14
	v_exp_f32_e32 v11, v10
	v_mul_f32_e32 v10, 0xbfb8aa3b, v15
	v_exp_f32_e32 v27, v10
	v_pk_fma_f32 v[28:29], v[64:65], v[18:19], v[28:29]
	v_lshlrev_b32_e32 v36, 16, v4
	v_and_b32_e32 v37, 0xffff0000, v4
	v_add_f32_e32 v11, 1.0, v11
	v_pk_fma_f32 v[28:29], v[68:69], v[36:37], v[28:29]
	v_cvt_pk_bf16_f32 v10, v12, v13
	v_rcp_f32_e32 v12, v11
	v_add_f32_e32 v11, 1.0, v27
	v_mul_f32_e32 v13, 0xbfb8aa3b, v29
	v_exp_f32_e32 v27, v13
	v_rcp_f32_e32 v13, v11
	v_mul_f32_e32 v4, 0xbfb8aa3b, v28
	v_exp_f32_e32 v4, v4
	v_pk_mul_f32 v[12:13], v[14:15], v[12:13]
	s_nop 0
	v_cvt_pk_bf16_f32 v11, v12, v13
	ds_write_b128 v30, v[8:11] offset:256
	v_pk_fma_f32 v[10:11], v[58:59], v[20:21], v[62:63]
	v_add_f32_e32 v4, 1.0, v4
	v_pk_fma_f32 v[10:11], v[66:67], v[22:23], v[10:11]
	v_lshlrev_b32_e32 v12, 16, v5
	v_and_b32_e32 v13, 0xffff0000, v5
	v_rcp_f32_e32 v38, v4
	v_add_f32_e32 v4, 1.0, v27
	v_pk_fma_f32 v[10:11], v[70:71], v[12:13], v[10:11]
	v_rcp_f32_e32 v39, v4
	v_mul_f32_e32 v4, 0xbfb8aa3b, v10
	v_exp_f32_e32 v5, v4
	v_mul_f32_e32 v4, 0xbfb8aa3b, v11
	v_exp_f32_e32 v14, v4
	v_pk_mul_f32 v[8:9], v[28:29], v[38:39]
	v_add_f32_e32 v5, 1.0, v5
	v_cvt_pk_bf16_f32 v4, v8, v9
	v_rcp_f32_e32 v8, v5
	v_add_f32_e32 v5, 1.0, v14
	v_pk_fma_f32 v[14:15], v[40:41], v[72:73], v[48:49]
	v_rcp_f32_e32 v9, v5
	v_pk_fma_f32 v[14:15], v[52:53], v[24:25], v[14:15]
	v_lshlrev_b32_e32 v20, 16, v6
	v_and_b32_e32 v21, 0xffff0000, v6
	v_pk_fma_f32 v[14:15], v[44:45], v[20:21], v[14:15]
	v_pk_mul_f32 v[8:9], v[10:11], v[8:9]
	v_mul_f32_e32 v5, 0xbfb8aa3b, v14
	v_exp_f32_e32 v5, v5
	v_mul_f32_e32 v6, 0xbfb8aa3b, v15
	v_exp_f32_e32 v27, v6
	v_pk_fma_f32 v[10:11], v[42:43], v[74:75], v[50:51]
	v_lshlrev_b32_e32 v28, 16, v7
	v_pk_fma_f32 v[10:11], v[54:55], v[16:17], v[10:11]
	v_and_b32_e32 v29, 0xffff0000, v7
	v_pk_fma_f32 v[10:11], v[46:47], v[28:29], v[10:11]
	v_add_f32_e32 v5, 1.0, v5
	v_mul_f32_e32 v7, 0xbfb8aa3b, v10
	v_rcp_f32_e32 v6, v5
	v_add_f32_e32 v5, 1.0, v27
	v_exp_f32_e32 v27, v7
	v_mul_f32_e32 v7, 0xbfb8aa3b, v11
	v_exp_f32_e32 v31, v7
	v_rcp_f32_e32 v7, v5
	v_add_f32_e32 v5, 1.0, v27
	v_rcp_f32_e32 v38, v5
	v_add_f32_e32 v5, 1.0, v31
	v_rcp_f32_e32 v39, v5
	v_cvt_pk_bf16_f32 v5, v8, v9
	v_pk_mul_f32 v[6:7], v[14:15], v[6:7]
	v_and_b32_e32 v15, 0xffff0000, v1
	v_pk_mul_f32 v[8:9], v[10:11], v[38:39]
	v_cvt_pk_bf16_f32 v6, v6, v7
	v_cvt_pk_bf16_f32 v7, v8, v9
	v_pk_fma_f32 v[8:9], v[56:57], v[18:19], v[60:61]
	v_lshlrev_b32_e32 v10, 16, v0
	v_pk_fma_f32 v[8:9], v[64:65], v[36:37], v[8:9]
	v_and_b32_e32 v11, 0xffff0000, v0
	v_pk_fma_f32 v[8:9], v[68:69], v[10:11], v[8:9]
	ds_write_b128 v30, v[4:7] offset:320
	v_mul_f32_e32 v0, 0xbfb8aa3b, v8
	v_exp_f32_e32 v0, v0
	v_mul_f32_e32 v14, 0xbfb8aa3b, v9
	v_exp_f32_e32 v14, v14
	v_pk_fma_f32 v[6:7], v[58:59], v[22:23], v[62:63]
	v_add_f32_e32 v0, 1.0, v0
	v_rcp_f32_e32 v4, v0
	v_add_f32_e32 v0, 1.0, v14
	v_pk_fma_f32 v[6:7], v[66:67], v[12:13], v[6:7]
	v_lshlrev_b32_e32 v14, 16, v1
	v_pk_fma_f32 v[6:7], v[70:71], v[14:15], v[6:7]
	v_rcp_f32_e32 v5, v0
	v_mul_f32_e32 v0, 0xbfb8aa3b, v6
	v_exp_f32_e32 v18, v0
	v_mul_f32_e32 v0, 0xbfb8aa3b, v7
	v_exp_f32_e32 v19, v0
	v_pk_mul_f32 v[0:1], v[8:9], v[4:5]
	v_pk_fma_f32 v[8:9], v[40:41], v[24:25], v[48:49]
	v_add_f32_e32 v4, 1.0, v18
	v_add_f32_e32 v5, 1.0, v19
	v_pk_fma_f32 v[8:9], v[52:53], v[20:21], v[8:9]
; #define LAS __attribute__((address_space(3)))
; __device__ __forceinline__ unsigned cvtpk(float lo, float hi) { f32x2_t v = {lo, hi}; bf16x2_t b = __builtin_convertvector(v, bf16x2_t); return __builtin_bit_cast(unsigned, b); }
; __device__ __forceinline__ float lo16(unsigned u) { return __uint_as_float(u << 16); }
; template <class Put>
; __device__ __forceinline__ void conv_compute(const ConvRaw& R, const float* cw, const float* cb, int col0, int rg, const Put& put) {
;     const f32x4 w0a = *(const f32x4*)(cw + col0), w0b = *(const f32x4*)(cw + col0 + 4), w1a = *(const f32x4*)(cw + XBCW + col0), w1b = *(const f32x4*)(cw + XBCW + col0 + 4);
;     const f32x4 w2a = *(const f32x4*)(cw + 2 * XBCW + col0), w2b = *(const f32x4*)(cw + 2 * XBCW + col0 + 4), ba = *(const f32x4*)(cb + col0), bb = *(const f32x4*)(cb + col0 + 4);
;     const int r0 = 8 * rg;
; #pragma unroll
;     for (int rr = 0; rr < 8; ++rr) {
;         const u32x4 xm = R.r[rr], x0 = R.r[rr + 1], xp = R.r[rr + 2]; u32x4 o;
; #pragma unroll
;         for (int e = 0; e < 4; ++e) {
;             const float wl0 = e < 2 ? w0a[2 * e] : w0b[2 * e - 4], wh0 = e < 2 ? w0a[2 * e + 1] : w0b[2 * e - 3];
;             const float wl1 = e < 2 ? w1a[2 * e] : w1b[2 * e - 4], wh1 = e < 2 ? w1a[2 * e + 1] : w1b[2 * e - 3];
;             const float wl2 = e < 2 ? w2a[2 * e] : w2b[2 * e - 4], wh2 = e < 2 ? w2a[2 * e + 1] : w2b[2 * e - 3];
;             const float bl = e < 2 ? ba[2 * e] : bb[2 * e - 4], bh = e < 2 ? ba[2 * e + 1] : bb[2 * e - 3];
;             const float vl = bl + wl0 * lo16(xm[e]) + wl1 * lo16(x0[e]) + wl2 * lo16(xp[e]);
;             const float vh = bh + wh0 * hi16(xm[e]) + wh1 * hi16(x0[e]) + wh2 * hi16(xp[e]);
;             o[e] = cvtpk(silu_fast(vl), silu_fast(vh));
;         }
;         put(r0 + rr, o);
;     }
; }
; __device__ __forceinline__ void states_unit(Frame& F, const Ptrs& P, int b, int c, int g, int hh) {
;     ...
;     const int hl = wid >> 1, ph = wid & 1;
;     const int lbase = (int)(unsigned)(size_t)lds + ((lane >> 4) & 1) * 32 + (lane & 3) * 8 + (4 * hi + ((lane & 15) >> 2)) * 64;
;     const LAS float* Wf = (const LAS float*)(lds + L_VEC) + (hl * 2 + 0) * 512 + 384; const LAS float* Wb = (const LAS float*)(lds + L_VEC) + (hl * 2 + 1) * 512 + 384;
;     f32x16 af[4], ab[4];
; #pragma unroll
;     for (int i = 0; i < 4; ++i) { af[i] = f32x16{}; ab[i] = f32x16{}; }
	v_lshlrev_b32_e32 v18, 16, v2
	v_and_b32_e32 v19, 0xffff0000, v2
	v_pk_fma_f32 v[8:9], v[44:45], v[18:19], v[8:9]
	v_rcp_f32_e32 v4, v4
	v_mul_f32_e32 v2, 0xbfb8aa3b, v8
	v_exp_f32_e32 v2, v2
	v_mul_f32_e32 v22, 0xbfb8aa3b, v9
	v_exp_f32_e32 v23, v22
	v_rcp_f32_e32 v5, v5
	v_add_f32_e32 v2, 1.0, v2
	v_rcp_f32_e32 v22, v2
	v_add_f32_e32 v2, 1.0, v23
	v_rcp_f32_e32 v23, v2
	v_pk_mul_f32 v[4:5], v[6:7], v[4:5]
	v_pk_fma_f32 v[6:7], v[42:43], v[16:17], v[50:51]
	v_cvt_pk_bf16_f32 v0, v0, v1
	v_cvt_pk_bf16_f32 v1, v4, v5
	v_pk_mul_f32 v[4:5], v[8:9], v[22:23]
	v_pk_fma_f32 v[6:7], v[54:55], v[28:29], v[6:7]
	v_lshlrev_b32_e32 v8, 16, v3
	v_and_b32_e32 v9, 0xffff0000, v3
	v_pk_fma_f32 v[6:7], v[46:47], v[8:9], v[6:7]
	v_pk_fma_f32 v[22:23], v[56:57], v[36:37], v[60:61]
	v_mul_f32_e32 v2, 0xbfb8aa3b, v6
	v_exp_f32_e32 v3, v2
	v_mul_f32_e32 v2, 0xbfb8aa3b, v7
	v_exp_f32_e32 v16, v2
	v_cvt_pk_bf16_f32 v2, v4, v5
	v_add_f32_e32 v3, 1.0, v3
	v_rcp_f32_e32 v4, v3
	v_add_f32_e32 v3, 1.0, v16
	v_lshlrev_b32_e32 v16, 16, v34
	v_and_b32_e32 v17, 0xffff0000, v34
	v_pk_fma_f32 v[10:11], v[64:65], v[10:11], v[22:23]
	s_nop 0
	v_pk_fma_f32 v[10:11], v[68:69], v[16:17], v[10:11]
	s_nop 0
	v_mul_f32_e32 v5, 0xbfb8aa3b, v10
	v_exp_f32_e32 v16, v5
	v_mul_f32_e32 v5, 0xbfb8aa3b, v11
	v_exp_f32_e32 v17, v5
	v_rcp_f32_e32 v5, v3
	v_add_f32_e32 v3, 1.0, v16
	v_rcp_f32_e32 v16, v3
	v_add_f32_e32 v3, 1.0, v17
	v_pk_mul_f32 v[4:5], v[6:7], v[4:5]
	v_rcp_f32_e32 v17, v3
	v_cvt_pk_bf16_f32 v3, v4, v5
	v_pk_fma_f32 v[4:5], v[58:59], v[12:13], v[62:63]
	ds_write_b128 v30, v[0:3] offset:384
	v_lshlrev_b32_e32 v2, 16, v33
	v_and_b32_e32 v3, 0xffff0000, v33
	v_pk_fma_f32 v[4:5], v[66:67], v[14:15], v[4:5]
	v_pk_mul_f32 v[0:1], v[10:11], v[16:17]
	v_pk_fma_f32 v[2:3], v[70:71], v[2:3], v[4:5]
	v_pk_fma_f32 v[10:11], v[40:41], v[20:21], v[48:49]
	v_mul_f32_e32 v4, 0xbfb8aa3b, v2
	v_exp_f32_e32 v4, v4
	v_mul_f32_e32 v5, 0xbfb8aa3b, v3
	v_exp_f32_e32 v5, v5
	v_cvt_pk_bf16_f32 v0, v0, v1
	v_add_f32_e32 v1, 1.0, v4
	v_lshlrev_b32_e32 v6, 16, v32
	v_and_b32_e32 v7, 0xffff0000, v32
	v_pk_fma_f32 v[10:11], v[52:53], v[18:19], v[10:11]
	v_rcp_f32_e32 v4, v1
	v_add_f32_e32 v1, 1.0, v5
	v_pk_fma_f32 v[6:7], v[44:45], v[6:7], v[10:11]
	v_rcp_f32_e32 v5, v1
	v_mul_f32_e32 v1, 0xbfb8aa3b, v6
	v_exp_f32_e32 v1, v1
	v_mul_f32_e32 v10, 0xbfb8aa3b, v7
	v_exp_f32_e32 v10, v10
	v_pk_mul_f32 v[2:3], v[2:3], v[4:5]
	v_add_f32_e32 v1, 1.0, v1
	v_rcp_f32_e32 v4, v1
	v_add_f32_e32 v1, 1.0, v10
	v_pk_fma_f32 v[10:11], v[42:43], v[28:29], v[50:51]
	v_mov_b32_e32 v48, 0
	v_pk_fma_f32 v[8:9], v[54:55], v[8:9], v[10:11]
	v_lshlrev_b32_e32 v10, 16, v26
	v_and_b32_e32 v11, 0xffff0000, v26
	v_pk_fma_f32 v[8:9], v[46:47], v[10:11], v[8:9]
	v_mov_b32_e32 v49, v48
	v_mul_f32_e32 v5, 0xbfb8aa3b, v8
	v_exp_f32_e32 v10, v5
	v_mul_f32_e32 v5, 0xbfb8aa3b, v9
	v_exp_f32_e32 v11, v5
	v_rcp_f32_e32 v5, v1
	v_add_f32_e32 v1, 1.0, v10
	v_rcp_f32_e32 v10, v1
	v_add_f32_e32 v1, 1.0, v11
	v_rcp_f32_e32 v11, v1
	v_cvt_pk_bf16_f32 v1, v2, v3
	v_pk_mul_f32 v[2:3], v[6:7], v[4:5]
	v_mov_b32_e32 v50, v48
	v_pk_mul_f32 v[4:5], v[8:9], v[10:11]
	v_cvt_pk_bf16_f32 v2, v2, v3
	v_cvt_pk_bf16_f32 v3, v4, v5
	ds_write_b128 v30, v[0:3] offset:448
	v_lshlrev_b32_e32 v0, 1, v100
	v_lshlrev_b32_e32 v1, 3, v100
	v_lshlrev_b32_e32 v2, 8, v128
	v_and_b32_e32 v3, 0xc0, v141
	v_and_b32_e32 v0, 32, v0
	v_and_b32_e32 v1, 24, v1
	v_add3_u32 v4, v2, 0, v3
	v_add3_u32 v2, s76, v2, v3
	v_add3_u32 v143, v4, v0, v1
	v_add3_u32 v144, v2, v0, v1
	v_mov_b32_e32 v51, v48
	v_mov_b32_e32 v52, v48
	v_mov_b32_e32 v53, v48
	v_mov_b32_e32 v54, v48
	v_mov_b32_e32 v55, v48
	v_mov_b32_e32 v56, v48
	v_mov_b32_e32 v57, v48
	v_mov_b32_e32 v58, v48
	v_mov_b32_e32 v59, v48
	v_mov_b32_e32 v60, v48
	v_mov_b32_e32 v61, v48
	v_mov_b32_e32 v62, v48
	v_mov_b32_e32 v63, v48
	v_mov_b32_e32 v32, v48
	v_mov_b32_e32 v33, v48
	v_mov_b32_e32 v34, v48
	v_mov_b32_e32 v35, v48
	v_mov_b32_e32 v36, v48
	v_mov_b32_e32 v37, v48
	v_mov_b32_e32 v38, v48
	v_mov_b32_e32 v39, v48
	v_mov_b32_e32 v40, v48
	v_mov_b32_e32 v41, v48
	v_mov_b32_e32 v42, v48
	v_mov_b32_e32 v43, v48
	v_mov_b32_e32 v44, v48
	v_mov_b32_e32 v45, v48
	v_mov_b32_e32 v46, v48
	v_mov_b32_e32 v47, v48
	v_mov_b32_e32 v16, v48
	v_mov_b32_e32 v17, v48
	v_mov_b32_e32 v18, v48
	v_mov_b32_e32 v19, v48
	v_mov_b32_e32 v20, v48
	v_mov_b32_e32 v21, v48
	v_mov_b32_e32 v22, v48
	v_mov_b32_e32 v23, v48
	v_mov_b32_e32 v24, v48
	v_mov_b32_e32 v25, v48
	v_mov_b32_e32 v26, v48
	v_mov_b32_e32 v27, v48
	v_mov_b32_e32 v28, v48
	v_mov_b32_e32 v29, v48
	v_mov_b32_e32 v30, v48
	v_mov_b32_e32 v31, v48
	v_mov_b32_e32 v0, v48
	v_mov_b32_e32 v1, v48
	v_mov_b32_e32 v2, v48
	v_mov_b32_e32 v3, v48
	v_mov_b32_e32 v4, v48
	v_mov_b32_e32 v5, v48
	v_mov_b32_e32 v6, v48
	v_mov_b32_e32 v7, v48
	v_mov_b32_e32 v8, v48
	v_mov_b32_e32 v9, v48
	v_mov_b32_e32 v10, v48
	v_mov_b32_e32 v11, v48
	v_mov_b32_e32 v12, v48
	v_mov_b32_e32 v13, v48
	v_mov_b32_e32 v14, v48
	v_mov_b32_e32 v15, v48
	v_mov_b32_e32 v112, v48
	v_mov_b32_e32 v113, v48
	v_mov_b32_e32 v114, v48
	v_mov_b32_e32 v115, v48
	v_mov_b32_e32 v116, v48
	v_mov_b32_e32 v117, v48
	v_mov_b32_e32 v118, v48
	v_mov_b32_e32 v119, v48
	v_mov_b32_e32 v120, v48
	v_mov_b32_e32 v121, v48
	v_mov_b32_e32 v122, v48
	v_mov_b32_e32 v123, v48
	v_mov_b32_e32 v124, v48
	v_mov_b32_e32 v125, v48
	v_mov_b32_e32 v126, v48
	v_mov_b32_e32 v127, v48
	v_mov_b32_e32 v96, v48
	v_mov_b32_e32 v97, v48
	v_mov_b32_e32 v98, v48
	v_mov_b32_e32 v99, v48
	v_mov_b32_e32 v100, v48
	v_mov_b32_e32 v101, v48
	v_mov_b32_e32 v102, v48
	v_mov_b32_e32 v103, v48
	v_mov_b32_e32 v104, v48
	v_mov_b32_e32 v105, v48
	v_mov_b32_e32 v106, v48
	v_mov_b32_e32 v107, v48
	v_mov_b32_e32 v108, v48
	v_mov_b32_e32 v109, v48
	v_mov_b32_e32 v110, v48
	v_mov_b32_e32 v111, v48
	v_mov_b32_e32 v80, v48
	v_mov_b32_e32 v81, v48
	v_mov_b32_e32 v82, v48
	v_mov_b32_e32 v83, v48
	v_mov_b32_e32 v84, v48
	v_mov_b32_e32 v85, v48
	v_mov_b32_e32 v86, v48
	v_mov_b32_e32 v87, v48
	v_mov_b32_e32 v88, v48
	v_mov_b32_e32 v89, v48
	v_mov_b32_e32 v90, v48
	v_mov_b32_e32 v91, v48
	v_mov_b32_e32 v92, v48
	v_mov_b32_e32 v93, v48
	v_mov_b32_e32 v94, v48
	v_mov_b32_e32 v95, v48
	v_mov_b32_e32 v64, v48
	v_mov_b32_e32 v65, v48
	v_mov_b32_e32 v66, v48
	v_mov_b32_e32 v67, v48
	v_mov_b32_e32 v68, v48
	v_mov_b32_e32 v69, v48
	v_mov_b32_e32 v70, v48
	v_mov_b32_e32 v71, v48
	v_mov_b32_e32 v72, v48
	v_mov_b32_e32 v73, v48
	v_mov_b32_e32 v74, v48
	v_mov_b32_e32 v75, v48
	v_mov_b32_e32 v76, v48
	v_mov_b32_e32 v77, v48
	v_mov_b32_e32 v78, v48
	v_mov_b32_e32 v79, v48
	s_waitcnt lgkmcnt(0)
	s_barrier

; __device__ __forceinline__ unsigned cvtpk(float lo, float hi) { f32x2_t v = {lo, hi}; bf16x2_t b = __builtin_convertvector(v, bf16x2_t); return __builtin_bit_cast(unsigned, b); }
; __device__ __forceinline__ float lo16(unsigned u) { return __uint_as_float(u << 16); }
; __device__ __forceinline__ float hi16(unsigned u) { return __uint_as_float(u & 0xffff0000u); }
; __device__ __forceinline__ float silu_fast(float v) { return v * __builtin_amdgcn_rcpf(1.f + __builtin_amdgcn_exp2f(-v * LOG2E)); }
; __device__ __forceinline__ unsigned cvtpk(float lo, float hi) { f32x2_t v = {lo, hi}; bf16x2_t b = __builtin_convertvector(v, bf16x2_t); return __builtin_bit_cast(unsigned, b); }
; __device__ __forceinline__ float lo16(unsigned u) { return __uint_as_float(u << 16); }
; __device__ __forceinline__ float hi16(unsigned u) { return __uint_as_float(u & 0xffff0000u); }
; template <class Put>
; __device__ __forceinline__ void conv_compute(const ConvRaw& R, const float* cw, const float* cb, int col0, int rg, const Put& put) {
;     const f32x4 w0a = *(const f32x4*)(cw + col0), w0b = *(const f32x4*)(cw + col0 + 4), w1a = *(const f32x4*)(cw + XBCW + col0), w1b = *(const f32x4*)(cw + XBCW + col0 + 4);
;     const f32x4 w2a = *(const f32x4*)(cw + 2 * XBCW + col0), w2b = *(const f32x4*)(cw + 2 * XBCW + col0 + 4), ba = *(const f32x4*)(cb + col0), bb = *(const f32x4*)(cb + col0 + 4);
;     const int r0 = 8 * rg;
; #pragma unroll
;     for (int rr = 0; rr < 8; ++rr) {
;         const u32x4 xm = R.r[rr], x0 = R.r[rr + 1], xp = R.r[rr + 2]; u32x4 o;
; #pragma unroll
;         for (int e = 0; e < 4; ++e) {
;             const float wl0 = e < 2 ? w0a[2 * e] : w0b[2 * e - 4], wh0 = e < 2 ? w0a[2 * e + 1] : w0b[2 * e - 3];
;             const float wl1 = e < 2 ? w1a[2 * e] : w1b[2 * e - 4], wh1 = e < 2 ? w1a[2 * e + 1] : w1b[2 * e - 3];
;             const float wl2 = e < 2 ? w2a[2 * e] : w2b[2 * e - 4], wh2 = e < 2 ? w2a[2 * e + 1] : w2b[2 * e - 3];
;             const float bl = e < 2 ? ba[2 * e] : bb[2 * e - 4], bh = e < 2 ? ba[2 * e + 1] : bb[2 * e - 3];
;             const float vl = bl + wl0 * lo16(xm[e]) + wl1 * lo16(x0[e]) + wl2 * lo16(xp[e]);
;             const float vh = bh + wh0 * hi16(xm[e]) + wh1 * hi16(x0[e]) + wh2 * hi16(xp[e]);
;             o[e] = cvtpk(silu_fast(vl), silu_fast(vh));
;         }
;         put(r0 + rr, o);
;     }
; }
.Lst2_577:
	s_or_b64 exec, exec, s[0:1]
	v_lshlrev_b64 v[44:45], 2, v[96:97]
	v_lshl_add_u64 v[46:47], s[24:25], 0, v[44:45]
	global_load_dwordx4 v[40:43], v[46:47], off offset:16 nt
	global_load_dwordx4 v[56:59], v[46:47], off nt
	v_lshl_add_u64 v[46:47], s[26:27], 0, v[44:45]
	global_load_dwordx4 v[60:63], v[46:47], off nt
	global_load_dwordx4 v[48:51], v[46:47], off offset:16 nt
	v_lshl_add_u64 v[46:47], s[22:23], 0, v[44:45]
	global_load_dwordx4 v[64:67], v[46:47], off nt
	global_load_dwordx4 v[52:55], v[46:47], off offset:16 nt
	v_lshl_add_u64 v[44:45], s[28:29], 0, v[44:45]
	global_load_dwordx4 v[68:71], v[44:45], off nt
	s_nop 0
	global_load_dwordx4 v[44:47], v[44:45], off offset:16 nt
	v_or_b32_e32 v80, s84, v102
	v_cmp_eq_u32_e32 vcc, 15, v102
	v_lshlrev_b32_e32 v82, 1, v101
	v_lshrrev_b32_e32 v83, 1, v102
	v_cmp_ne_u32_e64 s[0:1], 0, v80
	v_lshlrev_b32_e32 v74, 16, v24
	v_and_b32_e32 v75, 0xffff0000, v24
	v_lshlrev_b32_e32 v72, 16, v28
	v_and_b32_e32 v73, 0xffff0000, v28
	v_lshlrev_b32_e32 v76, 16, v25
	v_and_b32_e32 v77, 0xffff0000, v25
	v_lshlrev_b32_e32 v24, 16, v29
	v_and_b32_e32 v25, 0xffff0000, v29
	v_lshlrev_b32_e32 v28, 16, v30
	v_and_b32_e32 v29, 0xffff0000, v30
	v_cndmask_b32_e64 v30, 0, v35, s[0:1]
	s_and_b64 s[4:5], s[72:73], vcc
	v_and_or_b32 v35, v82, 8, v83
	v_lshlrev_b32_e32 v81, 14, v103
	v_lshlrev_b32_e32 v78, 16, v26
	v_and_b32_e32 v79, 0xffff0000, v26
	v_cndmask_b32_e64 v26, v39, 0, s[4:5]
	v_cndmask_b32_e64 v83, 0, v34, s[0:1]
	v_cndmask_b32_e64 v82, 0, v33, s[0:1]
	v_cndmask_b32_e64 v39, 0, v32, s[0:1]
	v_lshlrev_b32_e32 v35, 10, v35
	v_cndmask_b32_e64 v32, v38, 0, s[4:5]
	v_cndmask_b32_e64 v33, v37, 0, s[4:5]
	v_cndmask_b32_e64 v34, v36, 0, s[4:5]
	v_lshlrev_b32_e32 v36, 16, v30
	v_and_b32_e32 v37, 0xffff0000, v30
	v_add3_u32 v30, s82, v81, v35
	v_lshlrev_b32_e32 v38, 16, v39
	v_and_b32_e32 v39, 0xffff0000, v39
	v_lshlrev_b32_e32 v80, 16, v82
	v_and_b32_e32 v81, 0xffff0000, v82
	v_lshlrev_b32_e32 v82, 16, v83
	v_and_b32_e32 v83, 0xffff0000, v83
	v_lshlrev_b32_e32 v84, 9, v102
	v_lshlrev_b32_e32 v85, 4, v101
	v_and_b32_e32 v84, 0x200, v84
	v_and_b32_e32 v85, 48, v85
	v_add3_u32 v30, v30, v84, v85
	v_lshrrev_b32_e32 v128, 5, v104
	v_lshlrev_b32_e32 v141, 4, v100
	s_mov_b32 s2, 0
	v_lshl_add_u32 v142, v128, 4, 0
	s_waitcnt vmcnt(5)
	v_pk_fma_f32 v[38:39], v[56:57], v[38:39], v[60:61]
	v_pk_fma_f32 v[80:81], v[58:59], v[80:81], v[62:63]
	s_waitcnt vmcnt(4)
	v_pk_fma_f32 v[82:83], v[40:41], v[82:83], v[48:49]
	s_waitcnt vmcnt(3)
	v_pk_fma_f32 v[38:39], v[64:65], v[74:75], v[38:39]
	v_pk_fma_f32 v[80:81], v[66:67], v[76:77], v[80:81]
	s_waitcnt vmcnt(2)
	v_pk_fma_f32 v[82:83], v[52:53], v[78:79], v[82:83]
	s_waitcnt vmcnt(1)
	v_pk_fma_f32 v[38:39], v[68:69], v[72:73], v[38:39]
	v_pk_fma_f32 v[80:81], v[70:71], v[24:25], v[80:81]
	s_waitcnt vmcnt(0)
	v_pk_fma_f32 v[82:83], v[44:45], v[28:29], v[82:83]
	v_mul_f32_e32 v35, 0xbfb8aa3b, v38
	v_mul_f32_e32 v84, 0xbfb8aa3b, v39
	v_mul_f32_e32 v85, 0xbfb8aa3b, v80
	v_mul_f32_e32 v86, 0xbfb8aa3b, v81
	v_mul_f32_e32 v87, 0xbfb8aa3b, v82
	v_mul_f32_e32 v88, 0xbfb8aa3b, v83
	v_exp_f32_e32 v35, v35
	v_exp_f32_e32 v84, v84
	v_exp_f32_e32 v85, v85
	v_exp_f32_e32 v86, v86
	v_exp_f32_e32 v87, v87
	v_exp_f32_e32 v88, v88
	v_add_f32_e32 v35, 1.0, v35
	v_add_f32_e32 v89, 1.0, v84
	v_add_f32_e32 v90, 1.0, v85
	v_add_f32_e32 v91, 1.0, v86
	v_add_f32_e32 v92, 1.0, v87
	v_add_f32_e32 v93, 1.0, v88
	v_rcp_f32_e32 v84, v35
	v_rcp_f32_e32 v85, v89
	v_rcp_f32_e32 v86, v90
	v_rcp_f32_e32 v87, v91
	v_rcp_f32_e32 v88, v92
	v_rcp_f32_e32 v89, v93
	v_pk_fma_f32 v[90:91], v[42:43], v[36:37], v[50:51]
	v_pk_mul_f32 v[36:37], v[38:39], v[84:85]
	v_pk_mul_f32 v[38:39], v[80:81], v[86:87]
	v_pk_mul_f32 v[80:81], v[82:83], v[88:89]
	v_lshlrev_b32_e32 v82, 16, v27
	v_and_b32_e32 v83, 0xffff0000, v27
	v_cvt_pk_bf16_f32 v36, v36, v37
	v_cvt_pk_bf16_f32 v37, v38, v39
	v_pk_fma_f32 v[38:39], v[54:55], v[82:83], v[90:91]
	v_lshlrev_b32_e32 v84, 16, v31
	v_and_b32_e32 v85, 0xffff0000, v31
	v_pk_fma_f32 v[86:87], v[46:47], v[84:85], v[38:39]
	v_pk_fma_f32 v[74:75], v[56:57], v[74:75], v[60:61]
	v_mul_f32_e32 v27, 0xbfb8aa3b, v86
	v_exp_f32_e32 v27, v27
	v_mul_f32_e32 v31, 0xbfb8aa3b, v87
	v_exp_f32_e32 v31, v31
	v_pk_fma_f32 v[74:75], v[64:65], v[72:73], v[74:75]
	v_lshlrev_b32_e32 v88, 16, v20
	v_and_b32_e32 v89, 0xffff0000, v20
	v_pk_fma_f32 v[74:75], v[68:69], v[88:89], v[74:75]
	v_add_f32_e32 v27, 1.0, v27
	v_mul_f32_e32 v20, 0xbfb8aa3b, v74
	v_cvt_pk_bf16_f32 v38, v80, v81
	v_rcp_f32_e32 v80, v27
	v_add_f32_e32 v27, 1.0, v31
	v_exp_f32_e32 v20, v20
	v_mul_f32_e32 v31, 0xbfb8aa3b, v75
	v_exp_f32_e32 v31, v31
	v_rcp_f32_e32 v81, v27
	v_add_f32_e32 v20, 1.0, v20
	v_rcp_f32_e32 v90, v20
	v_add_f32_e32 v20, 1.0, v31
	v_rcp_f32_e32 v91, v20
	v_pk_mul_f32 v[80:81], v[86:87], v[80:81]
	s_nop 0
	v_cvt_pk_bf16_f32 v39, v80, v81
	ds_write_b128 v30, v[36:39]
	v_pk_fma_f32 v[38:39], v[58:59], v[76:77], v[62:63]
	v_pk_mul_f32 v[36:37], v[74:75], v[90:91]
	v_pk_fma_f32 v[38:39], v[66:67], v[24:25], v[38:39]
	v_lshlrev_b32_e32 v74, 16, v21
	v_and_b32_e32 v75, 0xffff0000, v21
	v_pk_fma_f32 v[38:39], v[70:71], v[74:75], v[38:39]
	v_pk_fma_f32 v[76:77], v[40:41], v[78:79], v[48:49]
	v_mul_f32_e32 v20, 0xbfb8aa3b, v38
	v_exp_f32_e32 v21, v20
	v_mul_f32_e32 v20, 0xbfb8aa3b, v39
	v_exp_f32_e32 v27, v20
	v_cvt_pk_bf16_f32 v20, v36, v37
	v_add_f32_e32 v21, 1.0, v21
	v_rcp_f32_e32 v36, v21
	v_add_f32_e32 v21, 1.0, v27
	v_rcp_f32_e32 v37, v21
	v_pk_fma_f32 v[76:77], v[52:53], v[28:29], v[76:77]
	v_lshlrev_b32_e32 v78, 16, v22
	v_and_b32_e32 v79, 0xffff0000, v22
	v_pk_fma_f32 v[76:77], v[44:45], v[78:79], v[76:77]
; __device__ __forceinline__ unsigned cvtpk(float lo, float hi) { f32x2_t v = {lo, hi}; bf16x2_t b = __builtin_convertvector(v, bf16x2_t); return __builtin_bit_cast(unsigned, b); }
; __device__ __forceinline__ float lo16(unsigned u) { return __uint_as_float(u << 16); }
; __device__ __forceinline__ float hi16(unsigned u) { return __uint_as_float(u & 0xffff0000u); }
; __device__ __forceinline__ float silu_fast(float v) { return v * __builtin_amdgcn_rcpf(1.f + __builtin_amdgcn_exp2f(-v * LOG2E)); }
; __device__ __forceinline__ unsigned cvtpk(float lo, float hi) { f32x2_t v = {lo, hi}; bf16x2_t b = __builtin_convertvector(v, bf16x2_t); return __builtin_bit_cast(unsigned, b); }
; __device__ __forceinline__ float lo16(unsigned u) { return __uint_as_float(u << 16); }
; __device__ __forceinline__ float hi16(unsigned u) { return __uint_as_float(u & 0xffff0000u); }
; template <class Put>
; __device__ __forceinline__ void conv_compute(const ConvRaw& R, const float* cw, const float* cb, int col0, int rg, const Put& put) {
;     const f32x4 w0a = *(const f32x4*)(cw + col0), w0b = *(const f32x4*)(cw + col0 + 4), w1a = *(const f32x4*)(cw + XBCW + col0), w1b = *(const f32x4*)(cw + XBCW + col0 + 4);
;     const f32x4 w2a = *(const f32x4*)(cw + 2 * XBCW + col0), w2b = *(const f32x4*)(cw + 2 * XBCW + col0 + 4), ba = *(const f32x4*)(cb + col0), bb = *(const f32x4*)(cb + col0 + 4);
;     const int r0 = 8 * rg;
; #pragma unroll
;     for (int rr = 0; rr < 8; ++rr) {
;         const u32x4 xm = R.r[rr], x0 = R.r[rr + 1], xp = R.r[rr + 2]; u32x4 o;
; #pragma unroll
;         for (int e = 0; e < 4; ++e) {
;             const float wl0 = e < 2 ? w0a[2 * e] : w0b[2 * e - 4], wh0 = e < 2 ? w0a[2 * e + 1] : w0b[2 * e - 3];
;             const float wl1 = e < 2 ? w1a[2 * e] : w1b[2 * e - 4], wh1 = e < 2 ? w1a[2 * e + 1] : w1b[2 * e - 3];
;             const float wl2 = e < 2 ? w2a[2 * e] : w2b[2 * e - 4], wh2 = e < 2 ? w2a[2 * e + 1] : w2b[2 * e - 3];
;             const float bl = e < 2 ? ba[2 * e] : bb[2 * e - 4], bh = e < 2 ? ba[2 * e + 1] : bb[2 * e - 3];
;             const float vl = bl + wl0 * lo16(xm[e]) + wl1 * lo16(x0[e]) + wl2 * lo16(xp[e]);
;             const float vh = bh + wh0 * hi16(xm[e]) + wh1 * hi16(x0[e]) + wh2 * hi16(xp[e]);
;             o[e] = cvtpk(silu_fast(vl), silu_fast(vh));
;         }
;         put(r0 + rr, o);
;     }
; }
	v_pk_mul_f32 v[36:37], v[38:39], v[36:37]
	v_mul_f32_e32 v21, 0xbfb8aa3b, v76
	v_exp_f32_e32 v21, v21
	v_mul_f32_e32 v22, 0xbfb8aa3b, v77
	v_exp_f32_e32 v27, v22
	v_pk_fma_f32 v[38:39], v[42:43], v[82:83], v[50:51]
	v_lshlrev_b32_e32 v80, 16, v23
	v_pk_fma_f32 v[38:39], v[54:55], v[84:85], v[38:39]
	v_and_b32_e32 v81, 0xffff0000, v23
	v_pk_fma_f32 v[38:39], v[46:47], v[80:81], v[38:39]
	v_add_f32_e32 v21, 1.0, v21
	v_mul_f32_e32 v23, 0xbfb8aa3b, v38
	v_rcp_f32_e32 v22, v21
	v_add_f32_e32 v21, 1.0, v27
	v_exp_f32_e32 v27, v23
	v_mul_f32_e32 v23, 0xbfb8aa3b, v39
	v_exp_f32_e32 v31, v23
	v_rcp_f32_e32 v23, v21
	v_add_f32_e32 v21, 1.0, v27
	v_rcp_f32_e32 v82, v21
	v_add_f32_e32 v21, 1.0, v31
	v_rcp_f32_e32 v83, v21
	v_cvt_pk_bf16_f32 v21, v36, v37
	v_pk_mul_f32 v[22:23], v[76:77], v[22:23]
	v_pk_fma_f32 v[28:29], v[40:41], v[28:29], v[48:49]
	v_pk_mul_f32 v[36:37], v[38:39], v[82:83]
	v_cvt_pk_bf16_f32 v22, v22, v23
	v_cvt_pk_bf16_f32 v23, v36, v37
	v_pk_fma_f32 v[36:37], v[56:57], v[72:73], v[60:61]
	v_lshlrev_b32_e32 v38, 16, v16
	v_pk_fma_f32 v[36:37], v[64:65], v[88:89], v[36:37]
	v_and_b32_e32 v39, 0xffff0000, v16
	v_pk_fma_f32 v[36:37], v[68:69], v[38:39], v[36:37]
	ds_write_b128 v30, v[20:23] offset:64
	v_mul_f32_e32 v16, 0xbfb8aa3b, v36
	v_exp_f32_e32 v16, v16
	v_mul_f32_e32 v27, 0xbfb8aa3b, v37
	v_exp_f32_e32 v27, v27
	v_pk_fma_f32 v[22:23], v[58:59], v[24:25], v[62:63]
	v_add_f32_e32 v16, 1.0, v16
	v_rcp_f32_e32 v20, v16
	v_add_f32_e32 v16, 1.0, v27
	v_rcp_f32_e32 v21, v16
	v_pk_fma_f32 v[22:23], v[66:67], v[74:75], v[22:23]
	v_lshlrev_b32_e32 v24, 16, v17
	v_and_b32_e32 v25, 0xffff0000, v17
	v_pk_fma_f32 v[22:23], v[70:71], v[24:25], v[22:23]
	v_pk_fma_f32 v[28:29], v[52:53], v[78:79], v[28:29]
	v_mul_f32_e32 v16, 0xbfb8aa3b, v22
	v_exp_f32_e32 v27, v16
	v_mul_f32_e32 v16, 0xbfb8aa3b, v23
	v_exp_f32_e32 v31, v16
	v_pk_mul_f32 v[16:17], v[36:37], v[20:21]
	v_lshlrev_b32_e32 v36, 16, v18
	v_and_b32_e32 v37, 0xffff0000, v18
	v_pk_fma_f32 v[28:29], v[44:45], v[36:37], v[28:29]
	v_add_f32_e32 v20, 1.0, v27
	v_mul_f32_e32 v18, 0xbfb8aa3b, v28
	v_exp_f32_e32 v18, v18
	v_mul_f32_e32 v27, 0xbfb8aa3b, v29
	v_exp_f32_e32 v27, v27
	v_add_f32_e32 v21, 1.0, v31
	v_add_f32_e32 v18, 1.0, v18
	v_rcp_f32_e32 v20, v20
	v_rcp_f32_e32 v21, v21
	v_rcp_f32_e32 v72, v18
	v_add_f32_e32 v18, 1.0, v27
	v_rcp_f32_e32 v73, v18
	v_pk_mul_f32 v[20:21], v[22:23], v[20:21]
	v_pk_fma_f32 v[22:23], v[42:43], v[84:85], v[50:51]
	v_cvt_pk_bf16_f32 v16, v16, v17
	v_cvt_pk_bf16_f32 v17, v20, v21
	v_pk_mul_f32 v[20:21], v[28:29], v[72:73]
	v_pk_fma_f32 v[22:23], v[54:55], v[80:81], v[22:23]
	v_lshlrev_b32_e32 v28, 16, v19
	v_and_b32_e32 v29, 0xffff0000, v19
	v_pk_fma_f32 v[22:23], v[46:47], v[28:29], v[22:23]
	v_pk_fma_f32 v[72:73], v[56:57], v[88:89], v[60:61]
	v_mul_f32_e32 v18, 0xbfb8aa3b, v22
	v_exp_f32_e32 v19, v18
	v_mul_f32_e32 v18, 0xbfb8aa3b, v23
	v_exp_f32_e32 v27, v18
	v_pk_fma_f32 v[72:73], v[64:65], v[38:39], v[72:73]
	v_lshlrev_b32_e32 v76, 16, v12
	v_and_b32_e32 v77, 0xffff0000, v12
	v_add_f32_e32 v19, 1.0, v19
	v_pk_fma_f32 v[72:73], v[68:69], v[76:77], v[72:73]
	v_cvt_pk_bf16_f32 v18, v20, v21
	v_rcp_f32_e32 v20, v19
	v_add_f32_e32 v19, 1.0, v27
	v_mul_f32_e32 v21, 0xbfb8aa3b, v73
	v_exp_f32_e32 v27, v21
	v_rcp_f32_e32 v21, v19
	v_mul_f32_e32 v12, 0xbfb8aa3b, v72
	v_exp_f32_e32 v12, v12
	v_pk_mul_f32 v[20:21], v[22:23], v[20:21]
	s_nop 0
	v_cvt_pk_bf16_f32 v19, v20, v21
	ds_write_b128 v30, v[16:19] offset:128
	v_pk_fma_f32 v[18:19], v[58:59], v[74:75], v[62:63]
	v_add_f32_e32 v12, 1.0, v12
	v_pk_fma_f32 v[18:19], v[66:67], v[24:25], v[18:19]
	v_lshlrev_b32_e32 v20, 16, v13
	v_and_b32_e32 v21, 0xffff0000, v13
	v_rcp_f32_e32 v82, v12
	v_add_f32_e32 v12, 1.0, v27
	v_pk_fma_f32 v[18:19], v[70:71], v[20:21], v[18:19]
	v_rcp_f32_e32 v83, v12
	v_mul_f32_e32 v12, 0xbfb8aa3b, v18
	v_exp_f32_e32 v13, v12
	v_mul_f32_e32 v12, 0xbfb8aa3b, v19
	v_exp_f32_e32 v22, v12
	v_pk_mul_f32 v[16:17], v[72:73], v[82:83]
	v_add_f32_e32 v13, 1.0, v13
	v_cvt_pk_bf16_f32 v12, v16, v17
	v_rcp_f32_e32 v16, v13
	v_add_f32_e32 v13, 1.0, v22
	v_pk_fma_f32 v[22:23], v[40:41], v[78:79], v[48:49]
	v_rcp_f32_e32 v17, v13
	v_pk_fma_f32 v[22:23], v[52:53], v[36:37], v[22:23]
	v_lshlrev_b32_e32 v72, 16, v14
	v_and_b32_e32 v73, 0xffff0000, v14
	v_pk_fma_f32 v[22:23], v[44:45], v[72:73], v[22:23]
	v_pk_mul_f32 v[16:17], v[18:19], v[16:17]
	v_mul_f32_e32 v13, 0xbfb8aa3b, v22
	v_exp_f32_e32 v13, v13
	v_mul_f32_e32 v14, 0xbfb8aa3b, v23
	v_exp_f32_e32 v27, v14
	v_pk_fma_f32 v[18:19], v[42:43], v[80:81], v[50:51]
	v_lshlrev_b32_e32 v74, 16, v15
	v_pk_fma_f32 v[18:19], v[54:55], v[28:29], v[18:19]
	v_and_b32_e32 v75, 0xffff0000, v15
	v_pk_fma_f32 v[18:19], v[46:47], v[74:75], v[18:19]
	v_add_f32_e32 v13, 1.0, v13
	v_mul_f32_e32 v15, 0xbfb8aa3b, v18
	v_rcp_f32_e32 v14, v13
	v_add_f32_e32 v13, 1.0, v27
	v_exp_f32_e32 v27, v15
	v_mul_f32_e32 v15, 0xbfb8aa3b, v19
	v_exp_f32_e32 v31, v15
	v_rcp_f32_e32 v15, v13
	v_add_f32_e32 v13, 1.0, v27
	v_rcp_f32_e32 v78, v13
	v_add_f32_e32 v13, 1.0, v31
	v_rcp_f32_e32 v79, v13
	v_cvt_pk_bf16_f32 v13, v16, v17
	v_pk_mul_f32 v[14:15], v[22:23], v[14:15]
	v_and_b32_e32 v23, 0xffff0000, v9
	v_pk_mul_f32 v[16:17], v[18:19], v[78:79]
	v_cvt_pk_bf16_f32 v14, v14, v15
	v_cvt_pk_bf16_f32 v15, v16, v17
	v_pk_fma_f32 v[16:17], v[56:57], v[38:39], v[60:61]
	v_lshlrev_b32_e32 v18, 16, v8
	v_pk_fma_f32 v[16:17], v[64:65], v[76:77], v[16:17]
	v_and_b32_e32 v19, 0xffff0000, v8
	v_pk_fma_f32 v[16:17], v[68:69], v[18:19], v[16:17]
	ds_write_b128 v30, v[12:15] offset:192
	v_mul_f32_e32 v8, 0xbfb8aa3b, v16
	v_exp_f32_e32 v8, v8
	v_mul_f32_e32 v22, 0xbfb8aa3b, v17
	v_exp_f32_e32 v22, v22
; __device__ __forceinline__ unsigned cvtpk(float lo, float hi) { f32x2_t v = {lo, hi}; bf16x2_t b = __builtin_convertvector(v, bf16x2_t); return __builtin_bit_cast(unsigned, b); }
; __device__ __forceinline__ float lo16(unsigned u) { return __uint_as_float(u << 16); }
; __device__ __forceinline__ float hi16(unsigned u) { return __uint_as_float(u & 0xffff0000u); }
; __device__ __forceinline__ float silu_fast(float v) { return v * __builtin_amdgcn_rcpf(1.f + __builtin_amdgcn_exp2f(-v * LOG2E)); }
; __device__ __forceinline__ unsigned cvtpk(float lo, float hi) { f32x2_t v = {lo, hi}; bf16x2_t b = __builtin_convertvector(v, bf16x2_t); return __builtin_bit_cast(unsigned, b); }
; __device__ __forceinline__ float lo16(unsigned u) { return __uint_as_float(u << 16); }
; __device__ __forceinline__ float hi16(unsigned u) { return __uint_as_float(u & 0xffff0000u); }
; template <class Put>
; __device__ __forceinline__ void conv_compute(const ConvRaw& R, const float* cw, const float* cb, int col0, int rg, const Put& put) {
;     const f32x4 w0a = *(const f32x4*)(cw + col0), w0b = *(const f32x4*)(cw + col0 + 4), w1a = *(const f32x4*)(cw + XBCW + col0), w1b = *(const f32x4*)(cw + XBCW + col0 + 4);
;     const f32x4 w2a = *(const f32x4*)(cw + 2 * XBCW + col0), w2b = *(const f32x4*)(cw + 2 * XBCW + col0 + 4), ba = *(const f32x4*)(cb + col0), bb = *(const f32x4*)(cb + col0 + 4);
;     const int r0 = 8 * rg;
; #pragma unroll
;     for (int rr = 0; rr < 8; ++rr) {
;         const u32x4 xm = R.r[rr], x0 = R.r[rr + 1], xp = R.r[rr + 2]; u32x4 o;
; #pragma unroll
;         for (int e = 0; e < 4; ++e) {
;             const float wl0 = e < 2 ? w0a[2 * e] : w0b[2 * e - 4], wh0 = e < 2 ? w0a[2 * e + 1] : w0b[2 * e - 3];
;             const float wl1 = e < 2 ? w1a[2 * e] : w1b[2 * e - 4], wh1 = e < 2 ? w1a[2 * e + 1] : w1b[2 * e - 3];
;             const float wl2 = e < 2 ? w2a[2 * e] : w2b[2 * e - 4], wh2 = e < 2 ? w2a[2 * e + 1] : w2b[2 * e - 3];
;             const float bl = e < 2 ? ba[2 * e] : bb[2 * e - 4], bh = e < 2 ? ba[2 * e + 1] : bb[2 * e - 3];
;             const float vl = bl + wl0 * lo16(xm[e]) + wl1 * lo16(x0[e]) + wl2 * lo16(xp[e]);
;             const float vh = bh + wh0 * hi16(xm[e]) + wh1 * hi16(x0[e]) + wh2 * hi16(xp[e]);
;             o[e] = cvtpk(silu_fast(vl), silu_fast(vh));
;         }
;         put(r0 + rr, o);
;     }
; }
	v_pk_fma_f32 v[14:15], v[58:59], v[24:25], v[62:63]
	v_add_f32_e32 v8, 1.0, v8
	v_rcp_f32_e32 v12, v8
	v_add_f32_e32 v8, 1.0, v22
	v_pk_fma_f32 v[14:15], v[66:67], v[20:21], v[14:15]
	v_lshlrev_b32_e32 v22, 16, v9
	v_pk_fma_f32 v[14:15], v[70:71], v[22:23], v[14:15]
	v_rcp_f32_e32 v13, v8
	v_mul_f32_e32 v8, 0xbfb8aa3b, v14
	v_exp_f32_e32 v24, v8
	v_mul_f32_e32 v8, 0xbfb8aa3b, v15
	v_exp_f32_e32 v25, v8
	v_pk_mul_f32 v[8:9], v[16:17], v[12:13]
	v_pk_fma_f32 v[16:17], v[40:41], v[36:37], v[48:49]
	v_add_f32_e32 v12, 1.0, v24
	v_add_f32_e32 v13, 1.0, v25
	v_pk_fma_f32 v[16:17], v[52:53], v[72:73], v[16:17]
	v_lshlrev_b32_e32 v24, 16, v10
	v_and_b32_e32 v25, 0xffff0000, v10
	v_pk_fma_f32 v[16:17], v[44:45], v[24:25], v[16:17]
	v_rcp_f32_e32 v12, v12
	v_mul_f32_e32 v10, 0xbfb8aa3b, v16
	v_exp_f32_e32 v10, v10
	v_mul_f32_e32 v27, 0xbfb8aa3b, v17
	v_exp_f32_e32 v27, v27
	v_rcp_f32_e32 v13, v13
	v_add_f32_e32 v10, 1.0, v10
	v_rcp_f32_e32 v36, v10
	v_add_f32_e32 v10, 1.0, v27
	v_rcp_f32_e32 v37, v10
	v_pk_mul_f32 v[12:13], v[14:15], v[12:13]
	v_pk_fma_f32 v[14:15], v[42:43], v[28:29], v[50:51]
	v_cvt_pk_bf16_f32 v8, v8, v9
	v_cvt_pk_bf16_f32 v9, v12, v13
	v_pk_mul_f32 v[12:13], v[16:17], v[36:37]
	v_pk_fma_f32 v[14:15], v[54:55], v[74:75], v[14:15]
	v_lshlrev_b32_e32 v16, 16, v11
	v_and_b32_e32 v17, 0xffff0000, v11
	v_pk_fma_f32 v[14:15], v[46:47], v[16:17], v[14:15]
	v_pk_fma_f32 v[28:29], v[56:57], v[76:77], v[60:61]
	v_mul_f32_e32 v10, 0xbfb8aa3b, v14
	v_exp_f32_e32 v11, v10
	v_mul_f32_e32 v10, 0xbfb8aa3b, v15
	v_exp_f32_e32 v27, v10
	v_pk_fma_f32 v[28:29], v[64:65], v[18:19], v[28:29]
	v_lshlrev_b32_e32 v36, 16, v4
	v_and_b32_e32 v37, 0xffff0000, v4
	v_add_f32_e32 v11, 1.0, v11
	v_pk_fma_f32 v[28:29], v[68:69], v[36:37], v[28:29]
	v_cvt_pk_bf16_f32 v10, v12, v13
	v_rcp_f32_e32 v12, v11
	v_add_f32_e32 v11, 1.0, v27
	v_mul_f32_e32 v13, 0xbfb8aa3b, v29
	v_exp_f32_e32 v27, v13
	v_rcp_f32_e32 v13, v11
	v_mul_f32_e32 v4, 0xbfb8aa3b, v28
	v_exp_f32_e32 v4, v4
	v_pk_mul_f32 v[12:13], v[14:15], v[12:13]
	s_nop 0
	v_cvt_pk_bf16_f32 v11, v12, v13
	ds_write_b128 v30, v[8:11] offset:256
	v_pk_fma_f32 v[10:11], v[58:59], v[20:21], v[62:63]
	v_add_f32_e32 v4, 1.0, v4
	v_pk_fma_f32 v[10:11], v[66:67], v[22:23], v[10:11]
	v_lshlrev_b32_e32 v12, 16, v5
	v_and_b32_e32 v13, 0xffff0000, v5
	v_rcp_f32_e32 v38, v4
	v_add_f32_e32 v4, 1.0, v27
	v_pk_fma_f32 v[10:11], v[70:71], v[12:13], v[10:11]
	v_rcp_f32_e32 v39, v4
	v_mul_f32_e32 v4, 0xbfb8aa3b, v10
	v_exp_f32_e32 v5, v4
	v_mul_f32_e32 v4, 0xbfb8aa3b, v11
	v_exp_f32_e32 v14, v4
	v_pk_mul_f32 v[8:9], v[28:29], v[38:39]
	v_add_f32_e32 v5, 1.0, v5
	v_cvt_pk_bf16_f32 v4, v8, v9
	v_rcp_f32_e32 v8, v5
	v_add_f32_e32 v5, 1.0, v14
	v_pk_fma_f32 v[14:15], v[40:41], v[72:73], v[48:49]
	v_rcp_f32_e32 v9, v5
	v_pk_fma_f32 v[14:15], v[52:53], v[24:25], v[14:15]
	v_lshlrev_b32_e32 v20, 16, v6
	v_and_b32_e32 v21, 0xffff0000, v6
	v_pk_fma_f32 v[14:15], v[44:45], v[20:21], v[14:15]
	v_pk_mul_f32 v[8:9], v[10:11], v[8:9]
	v_mul_f32_e32 v5, 0xbfb8aa3b, v14
	v_exp_f32_e32 v5, v5
	v_mul_f32_e32 v6, 0xbfb8aa3b, v15
	v_exp_f32_e32 v27, v6
	v_pk_fma_f32 v[10:11], v[42:43], v[74:75], v[50:51]
	v_lshlrev_b32_e32 v28, 16, v7
	v_pk_fma_f32 v[10:11], v[54:55], v[16:17], v[10:11]
	v_and_b32_e32 v29, 0xffff0000, v7
	v_pk_fma_f32 v[10:11], v[46:47], v[28:29], v[10:11]
	v_add_f32_e32 v5, 1.0, v5
	v_mul_f32_e32 v7, 0xbfb8aa3b, v10
	v_rcp_f32_e32 v6, v5
	v_add_f32_e32 v5, 1.0, v27
	v_exp_f32_e32 v27, v7
	v_mul_f32_e32 v7, 0xbfb8aa3b, v11
	v_exp_f32_e32 v31, v7
	v_rcp_f32_e32 v7, v5
	v_add_f32_e32 v5, 1.0, v27
	v_rcp_f32_e32 v38, v5
	v_add_f32_e32 v5, 1.0, v31
	v_rcp_f32_e32 v39, v5
	v_cvt_pk_bf16_f32 v5, v8, v9
	v_pk_mul_f32 v[6:7], v[14:15], v[6:7]
	v_and_b32_e32 v15, 0xffff0000, v1
	v_pk_mul_f32 v[8:9], v[10:11], v[38:39]
	v_cvt_pk_bf16_f32 v6, v6, v7
	v_cvt_pk_bf16_f32 v7, v8, v9
	v_pk_fma_f32 v[8:9], v[56:57], v[18:19], v[60:61]
	v_lshlrev_b32_e32 v10, 16, v0
	v_pk_fma_f32 v[8:9], v[64:65], v[36:37], v[8:9]
	v_and_b32_e32 v11, 0xffff0000, v0
	v_pk_fma_f32 v[8:9], v[68:69], v[10:11], v[8:9]
	ds_write_b128 v30, v[4:7] offset:320
	v_mul_f32_e32 v0, 0xbfb8aa3b, v8
	v_exp_f32_e32 v0, v0
	v_mul_f32_e32 v14, 0xbfb8aa3b, v9
	v_exp_f32_e32 v14, v14
	v_pk_fma_f32 v[6:7], v[58:59], v[22:23], v[62:63]
	v_add_f32_e32 v0, 1.0, v0
	v_rcp_f32_e32 v4, v0
	v_add_f32_e32 v0, 1.0, v14
	v_pk_fma_f32 v[6:7], v[66:67], v[12:13], v[6:7]
	v_lshlrev_b32_e32 v14, 16, v1
	v_pk_fma_f32 v[6:7], v[70:71], v[14:15], v[6:7]
	v_rcp_f32_e32 v5, v0
	v_mul_f32_e32 v0, 0xbfb8aa3b, v6
	v_exp_f32_e32 v18, v0
	v_mul_f32_e32 v0, 0xbfb8aa3b, v7
	v_exp_f32_e32 v19, v0
	v_pk_mul_f32 v[0:1], v[8:9], v[4:5]
	v_pk_fma_f32 v[8:9], v[40:41], v[24:25], v[48:49]
	v_add_f32_e32 v4, 1.0, v18
	v_add_f32_e32 v5, 1.0, v19
	v_pk_fma_f32 v[8:9], v[52:53], v[20:21], v[8:9]
	v_lshlrev_b32_e32 v18, 16, v2
	v_and_b32_e32 v19, 0xffff0000, v2
	v_pk_fma_f32 v[8:9], v[44:45], v[18:19], v[8:9]
	v_rcp_f32_e32 v4, v4
	v_mul_f32_e32 v2, 0xbfb8aa3b, v8
	v_exp_f32_e32 v2, v2
	v_mul_f32_e32 v22, 0xbfb8aa3b, v9
	v_exp_f32_e32 v23, v22
	v_rcp_f32_e32 v5, v5
	v_add_f32_e32 v2, 1.0, v2
	v_rcp_f32_e32 v22, v2
	v_add_f32_e32 v2, 1.0, v23
	v_rcp_f32_e32 v23, v2
	v_pk_mul_f32 v[4:5], v[6:7], v[4:5]
	v_pk_fma_f32 v[6:7], v[42:43], v[16:17], v[50:51]
	v_cvt_pk_bf16_f32 v0, v0, v1
	v_cvt_pk_bf16_f32 v1, v4, v5
	v_pk_mul_f32 v[4:5], v[8:9], v[22:23]
	v_pk_fma_f32 v[6:7], v[54:55], v[28:29], v[6:7]
	v_lshlrev_b32_e32 v8, 16, v3
	v_and_b32_e32 v9, 0xffff0000, v3
	v_pk_fma_f32 v[6:7], v[46:47], v[8:9], v[6:7]
	v_pk_fma_f32 v[22:23], v[56:57], v[36:37], v[60:61]
	v_mul_f32_e32 v2, 0xbfb8aa3b, v6
	v_exp_f32_e32 v3, v2
; #define LAS __attribute__((address_space(3)))
; __device__ __forceinline__ unsigned cvtpk(float lo, float hi) { f32x2_t v = {lo, hi}; bf16x2_t b = __builtin_convertvector(v, bf16x2_t); return __builtin_bit_cast(unsigned, b); }
; __device__ __forceinline__ float lo16(unsigned u) { return __uint_as_float(u << 16); }
; template <class Put>
; __device__ __forceinline__ void conv_compute(const ConvRaw& R, const float* cw, const float* cb, int col0, int rg, const Put& put) {
;     const f32x4 w0a = *(const f32x4*)(cw + col0), w0b = *(const f32x4*)(cw + col0 + 4), w1a = *(const f32x4*)(cw + XBCW + col0), w1b = *(const f32x4*)(cw + XBCW + col0 + 4);
;     const f32x4 w2a = *(const f32x4*)(cw + 2 * XBCW + col0), w2b = *(const f32x4*)(cw + 2 * XBCW + col0 + 4), ba = *(const f32x4*)(cb + col0), bb = *(const f32x4*)(cb + col0 + 4);
;     const int r0 = 8 * rg;
; #pragma unroll
;     for (int rr = 0; rr < 8; ++rr) {
;         const u32x4 xm = R.r[rr], x0 = R.r[rr + 1], xp = R.r[rr + 2]; u32x4 o;
; #pragma unroll
;         for (int e = 0; e < 4; ++e) {
;             const float wl0 = e < 2 ? w0a[2 * e] : w0b[2 * e - 4], wh0 = e < 2 ? w0a[2 * e + 1] : w0b[2 * e - 3];
;             const float wl1 = e < 2 ? w1a[2 * e] : w1b[2 * e - 4], wh1 = e < 2 ? w1a[2 * e + 1] : w1b[2 * e - 3];
;             const float wl2 = e < 2 ? w2a[2 * e] : w2b[2 * e - 4], wh2 = e < 2 ? w2a[2 * e + 1] : w2b[2 * e - 3];
;             const float bl = e < 2 ? ba[2 * e] : bb[2 * e - 4], bh = e < 2 ? ba[2 * e + 1] : bb[2 * e - 3];
;             const float vl = bl + wl0 * lo16(xm[e]) + wl1 * lo16(x0[e]) + wl2 * lo16(xp[e]);
;             const float vh = bh + wh0 * hi16(xm[e]) + wh1 * hi16(x0[e]) + wh2 * hi16(xp[e]);
;             o[e] = cvtpk(silu_fast(vl), silu_fast(vh));
;         }
;         put(r0 + rr, o);
;     }
; }
; __device__ __forceinline__ void states_unit(Frame& F, const Ptrs& P, int b, int c, int g, int hh) {
;     ...
;     const int hl = wid >> 1, ph = wid & 1;
;     const int lbase = (int)(unsigned)(size_t)lds + ((lane >> 4) & 1) * 32 + (lane & 3) * 8 + (4 * hi + ((lane & 15) >> 2)) * 64;
;     const LAS float* Wf = (const LAS float*)(lds + L_VEC) + (hl * 2 + 0) * 512 + 384; const LAS float* Wb = (const LAS float*)(lds + L_VEC) + (hl * 2 + 1) * 512 + 384;
;     f32x16 af[4], ab[4];
; #pragma unroll
;     for (int i = 0; i < 4; ++i) { af[i] = f32x16{}; ab[i] = f32x16{}; }
	v_mul_f32_e32 v2, 0xbfb8aa3b, v7
	v_exp_f32_e32 v16, v2
	v_cvt_pk_bf16_f32 v2, v4, v5
	v_add_f32_e32 v3, 1.0, v3
	v_rcp_f32_e32 v4, v3
	v_add_f32_e32 v3, 1.0, v16
	v_lshlrev_b32_e32 v16, 16, v34
	v_and_b32_e32 v17, 0xffff0000, v34
	v_pk_fma_f32 v[10:11], v[64:65], v[10:11], v[22:23]
	s_nop 0
	v_pk_fma_f32 v[10:11], v[68:69], v[16:17], v[10:11]
	s_nop 0
	v_mul_f32_e32 v5, 0xbfb8aa3b, v10
	v_exp_f32_e32 v16, v5
	v_mul_f32_e32 v5, 0xbfb8aa3b, v11
	v_exp_f32_e32 v17, v5
	v_rcp_f32_e32 v5, v3
	v_add_f32_e32 v3, 1.0, v16
	v_rcp_f32_e32 v16, v3
	v_add_f32_e32 v3, 1.0, v17
	v_pk_mul_f32 v[4:5], v[6:7], v[4:5]
	v_rcp_f32_e32 v17, v3
	v_cvt_pk_bf16_f32 v3, v4, v5
	v_pk_fma_f32 v[4:5], v[58:59], v[12:13], v[62:63]
	ds_write_b128 v30, v[0:3] offset:384
	v_lshlrev_b32_e32 v2, 16, v33
	v_and_b32_e32 v3, 0xffff0000, v33
	v_pk_fma_f32 v[4:5], v[66:67], v[14:15], v[4:5]
	v_pk_mul_f32 v[0:1], v[10:11], v[16:17]
	v_pk_fma_f32 v[2:3], v[70:71], v[2:3], v[4:5]
	v_pk_fma_f32 v[10:11], v[40:41], v[20:21], v[48:49]
	v_mul_f32_e32 v4, 0xbfb8aa3b, v2
	v_exp_f32_e32 v4, v4
	v_mul_f32_e32 v5, 0xbfb8aa3b, v3
	v_exp_f32_e32 v5, v5
	v_cvt_pk_bf16_f32 v0, v0, v1
	v_add_f32_e32 v1, 1.0, v4
	v_lshlrev_b32_e32 v6, 16, v32
	v_and_b32_e32 v7, 0xffff0000, v32
	v_pk_fma_f32 v[10:11], v[52:53], v[18:19], v[10:11]
	v_rcp_f32_e32 v4, v1
	v_add_f32_e32 v1, 1.0, v5
	v_pk_fma_f32 v[6:7], v[44:45], v[6:7], v[10:11]
	v_rcp_f32_e32 v5, v1
	v_mul_f32_e32 v1, 0xbfb8aa3b, v6
	v_exp_f32_e32 v1, v1
	v_mul_f32_e32 v10, 0xbfb8aa3b, v7
	v_exp_f32_e32 v10, v10
	v_pk_mul_f32 v[2:3], v[2:3], v[4:5]
	v_add_f32_e32 v1, 1.0, v1
	v_rcp_f32_e32 v4, v1
	v_add_f32_e32 v1, 1.0, v10
	v_pk_fma_f32 v[10:11], v[42:43], v[28:29], v[50:51]
	v_mov_b32_e32 v48, 0
	v_pk_fma_f32 v[8:9], v[54:55], v[8:9], v[10:11]
	v_lshlrev_b32_e32 v10, 16, v26
	v_and_b32_e32 v11, 0xffff0000, v26
	v_pk_fma_f32 v[8:9], v[46:47], v[10:11], v[8:9]
	v_mov_b32_e32 v49, v48
	v_mul_f32_e32 v5, 0xbfb8aa3b, v8
	v_exp_f32_e32 v10, v5
	v_mul_f32_e32 v5, 0xbfb8aa3b, v9
	v_exp_f32_e32 v11, v5
	v_rcp_f32_e32 v5, v1
	v_add_f32_e32 v1, 1.0, v10
	v_rcp_f32_e32 v10, v1
	v_add_f32_e32 v1, 1.0, v11
	v_rcp_f32_e32 v11, v1
	v_cvt_pk_bf16_f32 v1, v2, v3
	v_pk_mul_f32 v[2:3], v[6:7], v[4:5]
	v_mov_b32_e32 v50, v48
	v_pk_mul_f32 v[4:5], v[8:9], v[10:11]
	v_cvt_pk_bf16_f32 v2, v2, v3
	v_cvt_pk_bf16_f32 v3, v4, v5
	ds_write_b128 v30, v[0:3] offset:448
	v_lshlrev_b32_e32 v0, 1, v100
	v_lshlrev_b32_e32 v1, 3, v100
	v_lshlrev_b32_e32 v2, 8, v128
	v_and_b32_e32 v3, 0xc0, v141
	v_and_b32_e32 v0, 32, v0
	v_and_b32_e32 v1, 24, v1
	v_add3_u32 v4, v2, 0, v3
	v_add3_u32 v2, s76, v2, v3
	v_add3_u32 v143, v4, v0, v1
	v_add3_u32 v144, v2, v0, v1
	v_mov_b32_e32 v51, v48
	v_mov_b32_e32 v52, v48
	v_mov_b32_e32 v53, v48
	v_mov_b32_e32 v54, v48
	v_mov_b32_e32 v55, v48
	v_mov_b32_e32 v56, v48
	v_mov_b32_e32 v57, v48
	v_mov_b32_e32 v58, v48
	v_mov_b32_e32 v59, v48
	v_mov_b32_e32 v60, v48
	v_mov_b32_e32 v61, v48
	v_mov_b32_e32 v62, v48
	v_mov_b32_e32 v63, v48
	v_mov_b32_e32 v32, v48
	v_mov_b32_e32 v33, v48
	v_mov_b32_e32 v34, v48
	v_mov_b32_e32 v35, v48
	v_mov_b32_e32 v36, v48
	v_mov_b32_e32 v37, v48
	v_mov_b32_e32 v38, v48
	v_mov_b32_e32 v39, v48
	v_mov_b32_e32 v40, v48
	v_mov_b32_e32 v41, v48
	v_mov_b32_e32 v42, v48
	v_mov_b32_e32 v43, v48
	v_mov_b32_e32 v44, v48
	v_mov_b32_e32 v45, v48
	v_mov_b32_e32 v46, v48
	v_mov_b32_e32 v47, v48
	v_mov_b32_e32 v16, v48
	v_mov_b32_e32 v17, v48
	v_mov_b32_e32 v18, v48
	v_mov_b32_e32 v19, v48
	v_mov_b32_e32 v20, v48
	v_mov_b32_e32 v21, v48
	v_mov_b32_e32 v22, v48
	v_mov_b32_e32 v23, v48
	v_mov_b32_e32 v24, v48
	v_mov_b32_e32 v25, v48
	v_mov_b32_e32 v26, v48
	v_mov_b32_e32 v27, v48
	v_mov_b32_e32 v28, v48
	v_mov_b32_e32 v29, v48
	v_mov_b32_e32 v30, v48
	v_mov_b32_e32 v31, v48
	v_mov_b32_e32 v0, v48
	v_mov_b32_e32 v1, v48
	v_mov_b32_e32 v2, v48
	v_mov_b32_e32 v3, v48
	v_mov_b32_e32 v4, v48
	v_mov_b32_e32 v5, v48
	v_mov_b32_e32 v6, v48
	v_mov_b32_e32 v7, v48
	v_mov_b32_e32 v8, v48
	v_mov_b32_e32 v9, v48
	v_mov_b32_e32 v10, v48
	v_mov_b32_e32 v11, v48
	v_mov_b32_e32 v12, v48
	v_mov_b32_e32 v13, v48
	v_mov_b32_e32 v14, v48
	v_mov_b32_e32 v15, v48
	v_mov_b32_e32 v112, v48
	v_mov_b32_e32 v113, v48
	v_mov_b32_e32 v114, v48
	v_mov_b32_e32 v115, v48
	v_mov_b32_e32 v116, v48
	v_mov_b32_e32 v117, v48
	v_mov_b32_e32 v118, v48
	v_mov_b32_e32 v119, v48
	v_mov_b32_e32 v120, v48
	v_mov_b32_e32 v121, v48
	v_mov_b32_e32 v122, v48
	v_mov_b32_e32 v123, v48
	v_mov_b32_e32 v124, v48
	v_mov_b32_e32 v125, v48
	v_mov_b32_e32 v126, v48
	v_mov_b32_e32 v127, v48
	v_mov_b32_e32 v96, v48
	v_mov_b32_e32 v97, v48
	v_mov_b32_e32 v98, v48
	v_mov_b32_e32 v99, v48
	v_mov_b32_e32 v100, v48
	v_mov_b32_e32 v101, v48
	v_mov_b32_e32 v102, v48
	v_mov_b32_e32 v103, v48
	v_mov_b32_e32 v104, v48
	v_mov_b32_e32 v105, v48
	v_mov_b32_e32 v106, v48
	v_mov_b32_e32 v107, v48
	v_mov_b32_e32 v108, v48
	v_mov_b32_e32 v109, v48
	v_mov_b32_e32 v110, v48
	v_mov_b32_e32 v111, v48
	v_mov_b32_e32 v80, v48
	v_mov_b32_e32 v81, v48
	v_mov_b32_e32 v82, v48
	v_mov_b32_e32 v83, v48
	v_mov_b32_e32 v84, v48
	v_mov_b32_e32 v85, v48
	v_mov_b32_e32 v86, v48
	v_mov_b32_e32 v87, v48
	v_mov_b32_e32 v88, v48
	v_mov_b32_e32 v89, v48
	v_mov_b32_e32 v90, v48
	v_mov_b32_e32 v91, v48
	v_mov_b32_e32 v92, v48
	v_mov_b32_e32 v93, v48
	v_mov_b32_e32 v94, v48
	v_mov_b32_e32 v95, v48
	v_mov_b32_e32 v64, v48
	v_mov_b32_e32 v65, v48
	v_mov_b32_e32 v66, v48
	v_mov_b32_e32 v67, v48
	v_mov_b32_e32 v68, v48
	v_mov_b32_e32 v69, v48
	v_mov_b32_e32 v70, v48
	v_mov_b32_e32 v71, v48
	v_mov_b32_e32 v72, v48
	v_mov_b32_e32 v73, v48
	v_mov_b32_e32 v74, v48
	v_mov_b32_e32 v75, v48
	v_mov_b32_e32 v76, v48
	v_mov_b32_e32 v77, v48
	v_mov_b32_e32 v78, v48
	v_mov_b32_e32 v79, v48
	s_waitcnt lgkmcnt(0)
	s_barrier
